# S5 GLU weight bf16 copy re-tiled into contiguous 1KiB 16x32 MFMA fragment tiles (P0 writer + GLU loop reader addressing)
# speedup vs baseline: 1.0114x; 1.0094x over previous
.LBB0_464:
	v_ashrrev_i32_e32 v151, 31, v150
	v_lshlrev_b64 v[6:7], 9, v[150:151]
	v_lshl_add_u64 v[38:39], v[148:149], 0, v[6:7]
	global_load_dwordx4 v[40:43], v[38:39], off
	global_load_dwordx4 v[44:47], v[38:39], off offset:1024
	global_load_dwordx4 v[48:51], v[38:39], off offset:2048
	global_load_dwordx4 v[52:55], v[38:39], off offset:3072
	v_add_co_u32_e32 v6, vcc, s12, v38
	s_movk_i32 s4, 0x3000
	s_nop 0
	v_addc_co_u32_e32 v7, vcc, 0, v39, vcc
	v_add_co_u32_e32 v8, vcc, s68, v38
	v_add_u32_e32 v151, s22, v243
	s_nop 0
	v_addc_co_u32_e32 v9, vcc, 0, v39, vcc
	v_add_co_u32_e32 v14, vcc, s4, v38
	global_load_dwordx4 v[56:59], v[8:9], off offset:-4096
	global_load_dwordx4 v[60:63], v[6:7], off offset:1024
	global_load_dwordx4 v[64:67], v[6:7], off offset:2048
	global_load_dwordx4 v[68:71], v[6:7], off offset:3072
	global_load_dwordx4 v[26:29], v[8:9], off
	global_load_dwordx4 v[18:21], v[8:9], off offset:1024
	global_load_dwordx4 v[10:13], v[8:9], off offset:2048
	s_nop 0
	global_load_dwordx4 v[6:9], v[8:9], off offset:3072
	v_addc_co_u32_e32 v15, vcc, 0, v39, vcc
	v_add_co_u32_e32 v88, vcc, s69, v38
	s_movk_i32 s4, 0x5000
	s_nop 0
	v_addc_co_u32_e32 v89, vcc, 0, v39, vcc
	global_load_dwordx4 v[34:37], v[88:89], off offset:-4096
	global_load_dwordx4 v[30:33], v[14:15], off offset:1024
	global_load_dwordx4 v[22:25], v[14:15], off offset:2048
	s_nop 0
	global_load_dwordx4 v[14:17], v[14:15], off offset:3072
	ds_read_b128 v[158:161], v151 offset:14560
	ds_read_b128 v[162:165], v151 offset:31200
	ds_read_b128 v[166:169], v151 offset:47840
	ds_read_b128 v[170:173], v151 offset:64480
	ds_read_b128 v[174:177], v151 offset:12480
	v_ashrrev_i32_e32 v157, 31, v156
	v_add_u32_e32 v150, 64, v150
	v_add_u32_e32 v243, 32, v243
	s_waitcnt vmcnt(15)
	s_waitcnt lgkmcnt(4)
	v_mfma_f32_16x16x32_bf16 v[72:75], v[40:43], v[158:161], 0
	ds_read_b128 v[178:181], v151 offset:29120
	s_waitcnt lgkmcnt(4)
	v_mfma_f32_16x16x32_bf16 v[76:79], v[40:43], v[162:165], 0
	ds_read_b128 v[182:185], v151 offset:45760
	s_waitcnt lgkmcnt(4)
	v_mfma_f32_16x16x32_bf16 v[80:83], v[40:43], v[166:169], 0
	ds_read_b128 v[186:189], v151 offset:62400
	s_waitcnt lgkmcnt(4)
	v_mfma_f32_16x16x32_bf16 v[40:43], v[40:43], v[170:173], 0
	ds_read_b128 v[158:161], v151 offset:10400
	s_waitcnt vmcnt(14)
	s_waitcnt lgkmcnt(4)
	v_mfma_f32_16x16x32_bf16 v[72:75], v[44:47], v[174:177], v[72:75]
	ds_read_b128 v[162:165], v151 offset:27040
	s_waitcnt lgkmcnt(4)
	v_mfma_f32_16x16x32_bf16 v[76:79], v[44:47], v[178:181], v[76:79]
	ds_read_b128 v[166:169], v151 offset:43680
	s_waitcnt lgkmcnt(4)
	v_mfma_f32_16x16x32_bf16 v[80:83], v[44:47], v[182:185], v[80:83]
	ds_read_b128 v[170:173], v151 offset:60320
	s_waitcnt lgkmcnt(4)
	v_mfma_f32_16x16x32_bf16 v[40:43], v[44:47], v[186:189], v[40:43]
	ds_read_b128 v[174:177], v151 offset:8320
	s_waitcnt vmcnt(13)
	s_waitcnt lgkmcnt(4)
	v_mfma_f32_16x16x32_bf16 v[44:47], v[48:51], v[158:161], v[72:75]
	ds_read_b128 v[178:181], v151 offset:24960
	s_waitcnt lgkmcnt(4)
	v_mfma_f32_16x16x32_bf16 v[72:75], v[48:51], v[162:165], v[76:79]
	ds_read_b128 v[182:185], v151 offset:41600
	s_waitcnt lgkmcnt(4)
	v_mfma_f32_16x16x32_bf16 v[76:79], v[48:51], v[166:169], v[80:83]
	ds_read_b128 v[186:189], v151 offset:58240
	s_waitcnt lgkmcnt(4)
	v_mfma_f32_16x16x32_bf16 v[40:43], v[48:51], v[170:173], v[40:43]
	ds_read_b128 v[158:161], v151 offset:6240
	s_waitcnt vmcnt(12)
	s_waitcnt lgkmcnt(4)
	v_mfma_f32_16x16x32_bf16 v[44:47], v[52:55], v[174:177], v[44:47]
	ds_read_b128 v[162:165], v151 offset:22880
	s_waitcnt lgkmcnt(4)
	v_mfma_f32_16x16x32_bf16 v[48:51], v[52:55], v[178:181], v[72:75]
	ds_read_b128 v[166:169], v151 offset:39520
	s_waitcnt lgkmcnt(4)
	v_mfma_f32_16x16x32_bf16 v[72:75], v[52:55], v[182:185], v[76:79]
	ds_read_b128 v[170:173], v151 offset:56160
	s_waitcnt lgkmcnt(4)
	v_mfma_f32_16x16x32_bf16 v[40:43], v[52:55], v[186:189], v[40:43]
	ds_read_b128 v[174:177], v151 offset:4160
	s_waitcnt vmcnt(11)
	s_waitcnt lgkmcnt(4)
	v_mfma_f32_16x16x32_bf16 v[44:47], v[56:59], v[158:161], v[44:47]
	ds_read_b128 v[178:181], v151 offset:20800
	s_waitcnt lgkmcnt(4)
	v_mfma_f32_16x16x32_bf16 v[48:51], v[56:59], v[162:165], v[48:51]
	ds_read_b128 v[182:185], v151 offset:37440
	s_waitcnt lgkmcnt(4)
	v_mfma_f32_16x16x32_bf16 v[52:55], v[56:59], v[166:169], v[72:75]
	ds_read_b128 v[186:189], v151 offset:54080
	s_waitcnt lgkmcnt(4)
	v_mfma_f32_16x16x32_bf16 v[40:43], v[56:59], v[170:173], v[40:43]
	ds_read_b128 v[158:161], v151 offset:2080
	s_waitcnt vmcnt(10)
	s_waitcnt lgkmcnt(4)
	v_mfma_f32_16x16x32_bf16 v[44:47], v[60:63], v[174:177], v[44:47]
	ds_read_b128 v[162:165], v151 offset:18720
	s_waitcnt lgkmcnt(4)
	v_mfma_f32_16x16x32_bf16 v[48:51], v[60:63], v[178:181], v[48:51]
	ds_read_b128 v[166:169], v151 offset:35360
	s_waitcnt lgkmcnt(4)
	v_mfma_f32_16x16x32_bf16 v[52:55], v[60:63], v[182:185], v[52:55]
	ds_read_b128 v[170:173], v151 offset:52000
	s_waitcnt lgkmcnt(4)
	v_mfma_f32_16x16x32_bf16 v[40:43], v[60:63], v[186:189], v[40:43]
	ds_read_b128 v[174:177], v151
	s_waitcnt vmcnt(9)
	s_waitcnt lgkmcnt(4)
	v_mfma_f32_16x16x32_bf16 v[44:47], v[64:67], v[158:161], v[44:47]
	ds_read_b128 v[178:181], v151 offset:16640
	s_waitcnt lgkmcnt(4)
	v_mfma_f32_16x16x32_bf16 v[48:51], v[64:67], v[162:165], v[48:51]
	ds_read_b128 v[182:185], v151 offset:33280
	s_waitcnt lgkmcnt(4)
	v_mfma_f32_16x16x32_bf16 v[58:61], v[64:67], v[166:169], v[52:55]
	ds_read_b128 v[186:189], v151 offset:49920
	s_waitcnt lgkmcnt(4)
	v_mfma_f32_16x16x32_bf16 v[40:43], v[64:67], v[170:173], v[40:43]
	ds_read_b128 v[158:161], v151 offset:14560
	s_waitcnt vmcnt(8)
	s_waitcnt lgkmcnt(4)
	v_mfma_f32_16x16x32_bf16 v[54:57], v[68:71], v[174:177], v[44:47]
	ds_read_b128 v[162:165], v151 offset:31200
	v_add_co_u32_e32 v52, vcc, s4, v38
	s_waitcnt lgkmcnt(4)
	v_mfma_f32_16x16x32_bf16 v[44:47], v[68:71], v[178:181], v[48:51]
	ds_read_b128 v[166:169], v151 offset:47840
	v_addc_co_u32_e32 v53, vcc, 0, v39, vcc
	s_waitcnt lgkmcnt(4)
	v_mfma_f32_16x16x32_bf16 v[48:51], v[68:71], v[182:185], v[58:61]
	ds_read_b128 v[170:173], v151 offset:12480
	v_add_co_u32_e32 v102, vcc, s70, v38
	s_nop 1
	v_addc_co_u32_e32 v103, vcc, 0, v39, vcc
	s_waitcnt lgkmcnt(4)
	v_mfma_f32_16x16x32_bf16 v[40:43], v[68:71], v[186:189], v[40:43]
	ds_read_b128 v[174:177], v151 offset:29120
	global_load_dwordx4 v[70:73], v[88:89], off
	global_load_dwordx4 v[66:69], v[88:89], off offset:1024
	global_load_dwordx4 v[62:65], v[88:89], off offset:2048
	global_load_dwordx4 v[58:61], v[88:89], off offset:3072
	global_load_dwordx4 v[86:89], v[102:103], off offset:-4096
	global_load_dwordx4 v[82:85], v[52:53], off offset:1024
	global_load_dwordx4 v[78:81], v[52:53], off offset:2048
	global_load_dwordx4 v[74:77], v[52:53], off offset:3072
	s_waitcnt vmcnt(15)
	s_waitcnt lgkmcnt(4)
	v_mfma_f32_16x16x32_bf16 v[44:47], v[26:29], v[158:161], v[44:47]
	ds_read_b128 v[178:181], v151 offset:45760
	s_movk_i32 s4, 0x7000
	s_waitcnt lgkmcnt(4)
	v_mfma_f32_16x16x32_bf16 v[48:51], v[26:29], v[162:165], v[48:51]
	ds_read_b128 v[182:185], v151 offset:10400
	s_waitcnt lgkmcnt(4)
	v_mfma_f32_16x16x32_bf16 v[26:29], v[26:29], v[166:169], v[40:43]
	ds_read_b128 v[186:189], v151 offset:27040
	s_waitcnt vmcnt(14)
	s_waitcnt lgkmcnt(4)
	v_mfma_f32_16x16x32_bf16 v[40:43], v[18:21], v[170:173], v[44:47]
	ds_read_b128 v[158:161], v151 offset:43680
	s_waitcnt lgkmcnt(4)
	v_mfma_f32_16x16x32_bf16 v[44:47], v[18:21], v[174:177], v[48:51]
	ds_read_b128 v[162:165], v151 offset:8320
	s_waitcnt lgkmcnt(4)
	v_mfma_f32_16x16x32_bf16 v[18:21], v[18:21], v[178:181], v[26:29]
	ds_read_b128 v[166:169], v151 offset:24960
	s_waitcnt vmcnt(13)
	s_waitcnt lgkmcnt(4)
	v_mfma_f32_16x16x32_bf16 v[26:29], v[10:13], v[182:185], v[40:43]
	ds_read_b128 v[170:173], v151 offset:41600
	s_waitcnt lgkmcnt(4)
	v_mfma_f32_16x16x32_bf16 v[40:43], v[10:13], v[186:189], v[44:47]
	ds_read_b128 v[174:177], v151 offset:6240
	s_waitcnt lgkmcnt(4)
	v_mfma_f32_16x16x32_bf16 v[10:13], v[10:13], v[158:161], v[18:21]
	ds_read_b128 v[178:181], v151 offset:22880
	s_waitcnt vmcnt(12)
	s_waitcnt lgkmcnt(4)
	v_mfma_f32_16x16x32_bf16 v[18:21], v[6:9], v[162:165], v[26:29]
	ds_read_b128 v[182:185], v151 offset:39520
	s_waitcnt lgkmcnt(4)
	v_mfma_f32_16x16x32_bf16 v[26:29], v[6:9], v[166:169], v[40:43]
	ds_read_b128 v[186:189], v151 offset:4160
	s_waitcnt lgkmcnt(4)
	v_mfma_f32_16x16x32_bf16 v[6:9], v[6:9], v[170:173], v[10:13]
	ds_read_b128 v[158:161], v151 offset:20800
	s_waitcnt vmcnt(11)
	s_waitcnt lgkmcnt(4)
	v_mfma_f32_16x16x32_bf16 v[10:13], v[34:37], v[174:177], v[18:21]
	ds_read_b128 v[162:165], v151 offset:37440
	s_waitcnt lgkmcnt(4)
	v_mfma_f32_16x16x32_bf16 v[18:21], v[34:37], v[178:181], v[26:29]
	ds_read_b128 v[166:169], v151 offset:2080
	s_waitcnt lgkmcnt(4)
	v_mfma_f32_16x16x32_bf16 v[6:9], v[34:37], v[182:185], v[6:9]
	ds_read_b128 v[170:173], v151 offset:18720
	s_waitcnt vmcnt(10)
	s_waitcnt lgkmcnt(4)
	v_mfma_f32_16x16x32_bf16 v[10:13], v[30:33], v[186:189], v[10:13]
	ds_read_b128 v[174:177], v151 offset:35360
	s_waitcnt lgkmcnt(4)
	v_mfma_f32_16x16x32_bf16 v[18:21], v[30:33], v[158:161], v[18:21]
	ds_read_b128 v[178:181], v151
	s_waitcnt lgkmcnt(4)
	v_mfma_f32_16x16x32_bf16 v[6:9], v[30:33], v[162:165], v[6:9]
	ds_read_b128 v[182:185], v151 offset:16640
	s_waitcnt vmcnt(9)
	s_waitcnt lgkmcnt(4)
	v_mfma_f32_16x16x32_bf16 v[10:13], v[22:25], v[166:169], v[10:13]
	ds_read_b128 v[186:189], v151 offset:33280
	s_waitcnt lgkmcnt(4)
	v_mfma_f32_16x16x32_bf16 v[18:21], v[22:25], v[170:173], v[18:21]
	s_waitcnt lgkmcnt(3)
	v_mfma_f32_16x16x32_bf16 v[6:9], v[22:25], v[174:177], v[6:9]
	v_lshl_add_u64 v[26:27], v[156:157], 3, s[0:1]
	v_add_u32_e32 v156, 64, v156
	s_waitcnt vmcnt(8)
	s_waitcnt lgkmcnt(2)
	v_mfma_f32_16x16x32_bf16 v[50:53], v[14:17], v[178:181], v[10:13]
	s_waitcnt lgkmcnt(1)
	v_mfma_f32_16x16x32_bf16 v[106:109], v[14:17], v[182:185], v[18:21]
	global_load_dwordx4 v[90:93], v[102:103], off
	global_load_dwordx4 v[94:97], v[102:103], off offset:1024
	global_load_dwordx4 v[98:101], v[102:103], off offset:2048
	global_load_dwordx4 v[102:105], v[102:103], off offset:3072
	s_waitcnt lgkmcnt(0)
	v_mfma_f32_16x16x32_bf16 v[110:113], v[14:17], v[186:189], v[6:9]
	s_nop 2
	v_add_co_u32_e32 v6, vcc, s4, v38
	v_add_u32_e32 v8, s23, v239
	s_nop 0
	v_addc_co_u32_e32 v7, vcc, 0, v39, vcc
	global_load_dwordx4 v[118:121], v[6:7], off
	global_load_dwordx4 v[122:125], v[6:7], off offset:1024
	global_load_dwordx4 v[126:129], v[6:7], off offset:2048
	global_load_dwordx4 v[130:133], v[6:7], off offset:3072
	global_load_dwordx4 v[46:49], v[152:153], off offset:-128
	v_add_u32_e32 v6, s23, v240
	v_ashrrev_i32_e32 v7, 31, v6
	v_lshl_add_u64 v[10:11], v[6:7], 3, s[96:97]
	v_ashrrev_i32_e32 v9, 31, v8
	global_load_dwordx2 v[218:219], v[10:11], off offset:8
	v_lshl_add_u64 v[10:11], v[8:9], 3, s[96:97]
	global_load_dwordx2 v[208:209], v[10:11], off offset:128
	v_add_u32_e32 v10, 17, v8
	v_add_u32_e32 v12, 17, v6
	v_ashrrev_i32_e32 v13, 31, v12
	v_ashrrev_i32_e32 v11, 31, v10
	v_lshl_add_u64 v[12:13], v[12:13], 3, s[96:97]
	v_lshl_add_u64 v[10:11], v[10:11], 3, s[96:97]
	global_load_dwordx4 v[114:117], v[26:27], off offset:16
	global_load_dwordx4 v[134:137], v[26:27], off
	global_load_dwordx2 v[214:215], v[12:13], off offset:8
	global_load_dwordx2 v[206:207], v[10:11], off offset:128
	v_add_u32_e32 v10, 34, v8
	v_add_u32_e32 v12, 34, v6
	v_ashrrev_i32_e32 v13, 31, v12
	v_ashrrev_i32_e32 v11, 31, v10
	v_lshl_add_u64 v[12:13], v[12:13], 3, s[96:97]
	v_lshl_add_u64 v[10:11], v[10:11], 3, s[96:97]
	global_load_dwordx2 v[220:221], v[12:13], off offset:8
	global_load_dwordx2 v[212:213], v[10:11], off offset:128
	v_add_u32_e32 v10, 51, v8
	v_add_u32_e32 v12, 51, v6
	v_ashrrev_i32_e32 v13, 31, v12
	v_ashrrev_i32_e32 v11, 31, v10
	v_lshl_add_u64 v[12:13], v[12:13], 3, s[96:97]
	v_lshl_add_u64 v[10:11], v[10:11], 3, s[96:97]
	global_load_dwordx2 v[216:217], v[12:13], off offset:8
	global_load_dwordx2 v[210:211], v[10:11], off offset:128
	global_load_dwordx4 v[34:37], v[152:153], off offset:-64
	v_add_u32_e32 v10, 0x110, v8
	v_add_u32_e32 v12, 0x110, v6
	v_ashrrev_i32_e32 v13, 31, v12
	v_ashrrev_i32_e32 v11, 31, v10
	v_lshl_add_u64 v[12:13], v[12:13], 3, s[96:97]
	v_lshl_add_u64 v[10:11], v[10:11], 3, s[96:97]
	global_load_dwordx2 v[202:203], v[12:13], off offset:8
	global_load_dwordx2 v[192:193], v[10:11], off offset:128
	global_load_dwordx4 v[38:41], v[26:27], off offset:144
	global_load_dwordx4 v[42:45], v[26:27], off offset:128
	v_add_u32_e32 v10, 0x121, v8
	v_add_u32_e32 v12, 0x121, v6
	v_ashrrev_i32_e32 v13, 31, v12
	v_ashrrev_i32_e32 v11, 31, v10
	v_lshl_add_u64 v[12:13], v[12:13], 3, s[96:97]
	v_lshl_add_u64 v[10:11], v[10:11], 3, s[96:97]
	global_load_dwordx2 v[198:199], v[12:13], off offset:8
	global_load_dwordx2 v[190:191], v[10:11], off offset:128
	v_add_u32_e32 v10, 0x132, v8
	v_add_u32_e32 v12, 0x132, v6
	v_ashrrev_i32_e32 v13, 31, v12
	v_ashrrev_i32_e32 v11, 31, v10
	v_lshl_add_u64 v[12:13], v[12:13], 3, s[96:97]
	v_lshl_add_u64 v[10:11], v[10:11], 3, s[96:97]
	global_load_dwordx2 v[204:205], v[12:13], off offset:8
	global_load_dwordx2 v[196:197], v[10:11], off offset:128
	v_add_u32_e32 v10, 0x143, v8
	v_add_u32_e32 v12, 0x143, v6
	v_ashrrev_i32_e32 v13, 31, v12
	v_ashrrev_i32_e32 v11, 31, v10
	v_lshl_add_u64 v[12:13], v[12:13], 3, s[96:97]
	v_lshl_add_u64 v[10:11], v[10:11], 3, s[96:97]
	global_load_dwordx2 v[200:201], v[12:13], off offset:8
	global_load_dwordx2 v[194:195], v[10:11], off offset:128
	global_load_dwordx4 v[14:17], v[152:153], off
	v_add_u32_e32 v10, 0x220, v8
	v_add_u32_e32 v12, 0x220, v6
	v_ashrrev_i32_e32 v13, 31, v12
	v_ashrrev_i32_e32 v11, 31, v10
	v_lshl_add_u64 v[12:13], v[12:13], 3, s[96:97]
	v_lshl_add_u64 v[10:11], v[10:11], 3, s[96:97]
	global_load_dwordx2 v[184:185], v[12:13], off offset:8
	global_load_dwordx2 v[178:179], v[10:11], off offset:128
	global_load_dwordx4 v[22:25], v[26:27], off offset:272
	global_load_dwordx4 v[30:33], v[26:27], off offset:256
	v_add_u32_e32 v10, 0x231, v8
	v_add_u32_e32 v12, 0x231, v6
	v_ashrrev_i32_e32 v13, 31, v12
	v_ashrrev_i32_e32 v11, 31, v10
	v_lshl_add_u64 v[12:13], v[12:13], 3, s[96:97]
	v_lshl_add_u64 v[10:11], v[10:11], 3, s[96:97]
	global_load_dwordx2 v[182:183], v[12:13], off offset:8
	global_load_dwordx2 v[172:173], v[10:11], off offset:128
	v_add_u32_e32 v10, 0x242, v8
	v_add_u32_e32 v12, 0x242, v6
	v_ashrrev_i32_e32 v13, 31, v12
	v_ashrrev_i32_e32 v11, 31, v10
	v_lshl_add_u64 v[12:13], v[12:13], 3, s[96:97]
	v_lshl_add_u64 v[10:11], v[10:11], 3, s[96:97]
	global_load_dwordx2 v[186:187], v[12:13], off offset:8
	global_load_dwordx2 v[180:181], v[10:11], off offset:128
	v_add_u32_e32 v10, 0x253, v8
	v_add_u32_e32 v12, 0x253, v6
	v_add_u32_e32 v18, 0x330, v8
	v_add_u32_e32 v20, 0x330, v6
	v_add_u32_e32 v140, 0x341, v8
	v_add_u32_e32 v142, 0x341, v6
	v_ashrrev_i32_e32 v13, 31, v12
	v_ashrrev_i32_e32 v11, 31, v10
	v_ashrrev_i32_e32 v21, 31, v20
	v_ashrrev_i32_e32 v19, 31, v18
	v_ashrrev_i32_e32 v143, 31, v142
	v_ashrrev_i32_e32 v141, 31, v140
	v_lshl_add_u64 v[12:13], v[12:13], 3, s[96:97]
	v_lshl_add_u64 v[10:11], v[10:11], 3, s[96:97]
	v_lshl_add_u64 v[20:21], v[20:21], 3, s[96:97]
	v_lshl_add_u64 v[18:19], v[18:19], 3, s[96:97]
	v_lshl_add_u64 v[142:143], v[142:143], 3, s[96:97]
	v_lshl_add_u64 v[140:141], v[140:141], 3, s[96:97]
	global_load_dwordx2 v[176:177], v[12:13], off offset:8
	global_load_dwordx2 v[170:171], v[10:11], off offset:128
	s_nop 0
	global_load_dwordx4 v[10:13], v[152:153], off offset:64
	global_load_dwordx2 v[162:163], v[20:21], off offset:8
	global_load_dwordx2 v[160:161], v[18:19], off offset:128
	s_nop 0
	global_load_dwordx4 v[18:21], v[26:27], off offset:400
	s_nop 0
	global_load_dwordx4 v[26:29], v[26:27], off offset:384
	s_addk_i32 s23, 0x440
	global_load_dwordx2 v[164:165], v[142:143], off offset:8
	global_load_dwordx2 v[158:159], v[140:141], off offset:128
	v_add_u32_e32 v142, 0x352, v6
	v_add_u32_e32 v6, 0x363, v6
	v_ashrrev_i32_e32 v7, 31, v6
	v_lshl_add_u64 v[6:7], v[6:7], 3, s[96:97]
	global_load_dwordx2 v[174:175], v[6:7], off offset:8
	v_add_u32_e32 v140, 0x352, v8
	v_add_u32_e32 v8, 0x363, v8
	v_ashrrev_i32_e32 v143, 31, v142
	v_ashrrev_i32_e32 v141, 31, v140
	v_ashrrev_i32_e32 v9, 31, v8
	v_lshl_add_u64 v[142:143], v[142:143], 3, s[96:97]
	v_lshl_add_u64 v[140:141], v[140:141], 3, s[96:97]
	v_lshl_add_u64 v[6:7], v[8:9], 3, s[96:97]
	global_load_dwordx2 v[168:169], v[142:143], off offset:8
	global_load_dwordx2 v[166:167], v[140:141], off offset:128
	global_load_dwordx2 v[188:189], v[6:7], off offset:128
	s_nop 0
	global_load_dwordx4 v[6:9], v[154:155], off
	ds_read_b128 v[244:247], v151 offset:14560
	ds_read_b128 v[140:143], v151 offset:31200
	s_waitcnt vmcnt(60) lgkmcnt(1)
	v_mfma_f32_16x16x32_bf16 v[106:109], v[70:73], v[244:247], v[106:109]
	v_lshl_add_u64 v[152:153], v[152:153], 0, s[14:15]
	v_lshl_add_u64 v[154:155], v[154:155], 0, 64
	s_cmpk_eq_i32 s23, 0x1100
	s_waitcnt lgkmcnt(0)
	v_mfma_f32_16x16x32_bf16 v[70:73], v[70:73], v[140:143], v[110:113]
	ds_read_b128 v[140:143], v151 offset:29120
	s_nop 1
	ds_read_b128 v[110:113], v151 offset:12480
	s_waitcnt vmcnt(59) lgkmcnt(0)
	v_mfma_f32_16x16x32_bf16 v[106:109], v[66:69], v[110:113], v[106:109]
	v_mfma_f32_16x16x32_bf16 v[66:69], v[66:69], v[140:143], v[70:73]
	ds_read_b128 v[140:143], v151 offset:27040
	s_nop 1
	ds_read_b128 v[70:73], v151 offset:10400
	s_waitcnt vmcnt(58) lgkmcnt(0)
	v_mfma_f32_16x16x32_bf16 v[106:109], v[62:65], v[70:73], v[106:109]
	v_mfma_f32_16x16x32_bf16 v[62:65], v[62:65], v[140:143], v[66:69]
	ds_read_b128 v[140:143], v151 offset:24960
	s_nop 1
	ds_read_b128 v[66:69], v151 offset:8320
	s_waitcnt vmcnt(57) lgkmcnt(0)
	v_mfma_f32_16x16x32_bf16 v[106:109], v[58:61], v[66:69], v[106:109]
	v_mfma_f32_16x16x32_bf16 v[58:61], v[58:61], v[140:143], v[62:65]
	ds_read_b128 v[140:143], v151 offset:6240
	s_waitcnt vmcnt(56) lgkmcnt(0)
	v_mfma_f32_16x16x32_bf16 v[62:65], v[86:89], v[140:143], v[106:109]
	s_nop 3
	ds_read_b128 v[106:109], v151 offset:22880
	s_waitcnt lgkmcnt(0)
	v_mfma_f32_16x16x32_bf16 v[58:61], v[86:89], v[106:109], v[58:61]
	ds_read_b128 v[86:89], v151 offset:4160
	ds_read_b128 v[106:109], v151 offset:20800
	s_waitcnt vmcnt(55) lgkmcnt(1)
	v_mfma_f32_16x16x32_bf16 v[62:65], v[82:85], v[86:89], v[62:65]
	s_waitcnt lgkmcnt(0)
	v_mfma_f32_16x16x32_bf16 v[58:61], v[82:85], v[106:109], v[58:61]
	ds_read_b128 v[82:85], v151 offset:2080
	ds_read_b128 v[106:109], v151 offset:18720
	s_waitcnt vmcnt(54) lgkmcnt(1)
	v_mfma_f32_16x16x32_bf16 v[62:65], v[78:81], v[82:85], v[62:65]
	s_waitcnt lgkmcnt(0)
	v_mfma_f32_16x16x32_bf16 v[58:61], v[78:81], v[106:109], v[58:61]
	ds_read_b128 v[78:81], v151
	ds_read_b128 v[106:109], v151 offset:16640
	s_waitcnt vmcnt(53) lgkmcnt(0)
	v_mfma_f32_16x16x32_bf16 v[58:61], v[74:77], v[106:109], v[58:61]
	s_waitcnt vmcnt(52)
	v_mfma_f32_16x16x32_bf16 v[58:61], v[90:93], v[244:247], v[58:61]
	s_waitcnt vmcnt(51)
	v_mfma_f32_16x16x32_bf16 v[58:61], v[94:97], v[110:113], v[58:61]
	s_waitcnt vmcnt(50)
	v_mfma_f32_16x16x32_bf16 v[58:61], v[98:101], v[70:73], v[58:61]
	s_waitcnt vmcnt(40)
	v_mov_b32_e32 v72, v134
	v_mov_b32_e32 v73, v136
	v_mov_b32_e32 v70, v114
	v_mfma_f32_16x16x32_bf16 v[58:61], v[102:105], v[66:69], v[58:61]
	v_mov_b32_e32 v71, v116
	v_mov_b32_e32 v136, v135
	v_mov_b32_e32 v116, v115
	v_mfma_f32_16x16x32_bf16 v[58:61], v[118:121], v[140:143], v[58:61]
	v_mfma_f32_16x16x32_bf16 v[58:61], v[122:125], v[86:89], v[58:61]
	v_mfma_f32_16x16x32_bf16 v[58:61], v[126:129], v[82:85], v[58:61]
	v_mfma_f32_16x16x32_bf16 v[62:65], v[74:77], v[78:81], v[62:65]
	s_waitcnt vmcnt(39)
	v_mov_b32_e32 v75, v214
	v_mov_b32_e32 v214, v219
	s_waitcnt vmcnt(35)
	v_mov_b32_e32 v77, v216
	v_mov_b32_e32 v216, v221
	v_mfma_f32_16x16x32_bf16 v[66:69], v[130:133], v[78:81], v[58:61]
	v_mov_b32_e32 v74, v218
	v_mov_b32_e32 v76, v220
	v_pk_mul_f32 v[80:81], v[216:217], v[70:71]
	v_pk_mul_f32 v[60:61], v[214:215], v[72:73]
	v_pk_mul_f32 v[58:59], v[214:215], v[136:137]
	v_pk_fma_f32 v[60:61], v[74:75], v[136:137], v[60:61]
	v_pk_mul_f32 v[78:79], v[216:217], v[116:117]
	v_pk_fma_f32 v[80:81], v[76:77], v[116:117], v[80:81]
	v_pk_fma_f32 v[58:59], v[74:75], v[72:73], v[58:59] neg_lo:[0,0,1] neg_hi:[0,0,1]
	v_pk_fma_f32 v[78:79], v[76:77], v[70:71], v[78:79] neg_lo:[0,0,1] neg_hi:[0,0,1]
	v_cvt_pk_bf16_f32 v59, v59, v61
	v_cvt_pk_bf16_f32 v61, v79, v81
	v_cvt_pk_bf16_f32 v58, v58, v60
	v_cvt_pk_bf16_f32 v60, v78, v80
	v_mov_b32_e32 v79, v206
	v_mov_b32_e32 v206, v209
	v_mfma_f32_16x16x32_bf16 v[54:57], v[46:49], v[58:61], v[54:57]
	v_mov_b32_e32 v78, v208
	v_pk_mul_f32 v[58:59], v[214:215], v[206:207]
	v_mov_b32_e32 v82, v212
	s_waitcnt vmcnt(34)
	v_mov_b32_e32 v83, v210
	v_mov_b32_e32 v210, v213
	v_pk_fma_f32 v[80:81], v[74:75], v[78:79], v[58:59] neg_lo:[0,0,1] neg_hi:[0,0,1]
	v_pk_mul_f32 v[58:59], v[214:215], v[78:79]
	v_pk_mul_f32 v[84:85], v[216:217], v[210:211]
	v_pk_mul_f32 v[86:87], v[216:217], v[82:83]
	v_pk_fma_f32 v[74:75], v[74:75], v[206:207], v[58:59]
	v_pk_fma_f32 v[84:85], v[76:77], v[82:83], v[84:85] neg_lo:[0,0,1] neg_hi:[0,0,1]
	v_pk_fma_f32 v[76:77], v[76:77], v[210:211], v[86:87]
	v_pk_mul_f32 v[60:61], v[72:73], v[74:75]
	v_pk_mul_f32 v[88:89], v[70:71], v[76:77]
	v_pk_mul_f32 v[58:59], v[136:137], v[74:75]
	v_pk_fma_f32 v[60:61], v[136:137], v[80:81], v[60:61]
	v_pk_mul_f32 v[86:87], v[116:117], v[76:77]
	v_pk_fma_f32 v[88:89], v[116:117], v[84:85], v[88:89]
	v_pk_fma_f32 v[58:59], v[72:73], v[80:81], v[58:59] neg_lo:[0,0,1] neg_hi:[0,0,1]
	v_pk_fma_f32 v[86:87], v[70:71], v[84:85], v[86:87] neg_lo:[0,0,1] neg_hi:[0,0,1]
	v_cvt_pk_bf16_f32 v59, v59, v61
	v_cvt_pk_bf16_f32 v61, v87, v89
	v_cvt_pk_bf16_f32 v58, v58, v60
	v_cvt_pk_bf16_f32 v60, v86, v88
	s_nop 1
	v_mfma_f32_16x16x32_bf16 v[58:61], v[46:49], v[58:61], v[50:53]
	s_nop 2
	v_mul_f32_e64 v52, v78, v74
	v_mul_f32_e64 v53, v79, v75
	v_pk_mul_f32 v[50:51], v[206:207], v[74:75]
	v_pk_fma_f32 v[52:53], v[206:207], v[80:81], v[52:53]
	v_pk_fma_f32 v[50:51], v[78:79], v[80:81], v[50:51] neg_lo:[0,0,1] neg_hi:[0,0,1]
	v_pk_mul_f32 v[74:75], v[136:137], v[52:53]
	v_pk_mul_f32 v[80:81], v[72:73], v[52:53]
	v_pk_mul_f32 v[86:87], v[206:207], v[52:53]
	v_pk_mul_f32 v[52:53], v[78:79], v[52:53]
	v_pk_fma_f32 v[74:75], v[72:73], v[50:51], v[74:75] neg_lo:[0,0,1] neg_hi:[0,0,1]
	v_pk_fma_f32 v[80:81], v[136:137], v[50:51], v[80:81]
	v_pk_fma_f32 v[86:87], v[78:79], v[50:51], v[86:87] neg_lo:[0,0,1] neg_hi:[0,0,1]
	v_pk_fma_f32 v[50:51], v[206:207], v[50:51], v[52:53]
	s_nop 0
	v_pk_mul_f32 v[52:53], v[136:137], v[50:51]
	v_pk_mul_f32 v[50:51], v[72:73], v[50:51]
	v_pk_fma_f32 v[78:79], v[72:73], v[86:87], v[52:53] neg_lo:[0,0,1] neg_hi:[0,0,1]
	v_pk_mul_f32 v[52:53], v[82:83], v[76:77]
	v_pk_fma_f32 v[72:73], v[136:137], v[86:87], v[50:51]
	v_pk_mul_f32 v[50:51], v[210:211], v[76:77]
	v_pk_fma_f32 v[52:53], v[210:211], v[84:85], v[52:53]
	v_pk_fma_f32 v[50:51], v[82:83], v[84:85], v[50:51] neg_lo:[0,0,1] neg_hi:[0,0,1]
	v_pk_mul_f32 v[84:85], v[70:71], v[52:53]
	v_pk_mul_f32 v[76:77], v[116:117], v[52:53]
	v_pk_fma_f32 v[84:85], v[116:117], v[50:51], v[84:85]
	v_pk_mul_f32 v[86:87], v[210:211], v[52:53]
	v_pk_mul_f32 v[52:53], v[82:83], v[52:53]
	v_pk_fma_f32 v[76:77], v[70:71], v[50:51], v[76:77] neg_lo:[0,0,1] neg_hi:[0,0,1]
	v_pk_fma_f32 v[86:87], v[82:83], v[50:51], v[86:87] neg_lo:[0,0,1] neg_hi:[0,0,1]
	v_pk_fma_f32 v[82:83], v[210:211], v[50:51], v[52:53]
	v_cvt_pk_bf16_f32 v53, v77, v85
	v_cvt_pk_bf16_f32 v52, v76, v84
	v_cvt_pk_bf16_f32 v51, v75, v81
	v_cvt_pk_bf16_f32 v50, v74, v80
	s_nop 1
	v_mfma_f32_16x16x32_bf16 v[62:65], v[46:49], v[50:53], v[62:65]
	v_mul_f32_e64 v52, v70, v82
	v_mul_f32_e64 v53, v71, v83
	v_pk_mul_f32 v[50:51], v[116:117], v[82:83]
	v_pk_fma_f32 v[52:53], v[116:117], v[86:87], v[52:53]
	v_pk_fma_f32 v[50:51], v[70:71], v[86:87], v[50:51] neg_lo:[0,0,1] neg_hi:[0,0,1]
	s_nop 0
	v_cvt_pk_bf16_f32 v53, v51, v53
	v_cvt_pk_bf16_f32 v51, v79, v73
	v_cvt_pk_bf16_f32 v52, v50, v52
	v_cvt_pk_bf16_f32 v50, v78, v72
	s_waitcnt vmcnt(28)
	v_mov_b32_e32 v75, v198
	v_mov_b32_e32 v70, v42
	v_mov_b32_e32 v71, v44
	v_mov_b32_e32 v198, v203
	s_waitcnt vmcnt(24)
	v_mov_b32_e32 v77, v200
	v_mov_b32_e32 v72, v38
	v_mov_b32_e32 v73, v40
	v_mov_b32_e32 v200, v205
	v_mfma_f32_16x16x32_bf16 v[66:69], v[46:49], v[50:53], v[66:69]
	v_mov_b32_e32 v74, v202
	v_mov_b32_e32 v44, v43
	v_pk_mul_f32 v[46:47], v[198:199], v[70:71]
	v_mov_b32_e32 v76, v204
	v_mov_b32_e32 v40, v39
	v_pk_mul_f32 v[48:49], v[200:201], v[72:73]
	v_pk_mul_f32 v[42:43], v[198:199], v[44:45]
	v_pk_fma_f32 v[46:47], v[74:75], v[44:45], v[46:47]
	v_pk_mul_f32 v[38:39], v[200:201], v[40:41]
	v_pk_fma_f32 v[48:49], v[76:77], v[40:41], v[48:49]
	v_pk_fma_f32 v[42:43], v[74:75], v[70:71], v[42:43] neg_lo:[0,0,1] neg_hi:[0,0,1]
	v_pk_fma_f32 v[38:39], v[76:77], v[72:73], v[38:39] neg_lo:[0,0,1] neg_hi:[0,0,1]
	s_nop 0
	v_cvt_pk_bf16_f32 v49, v39, v49
	v_cvt_pk_bf16_f32 v48, v38, v48
	v_cvt_pk_bf16_f32 v47, v43, v47
	v_cvt_pk_bf16_f32 v46, v42, v46
	v_mov_b32_e32 v38, v192
	v_mov_b32_e32 v39, v190
	v_mov_b32_e32 v190, v193
	v_mfma_f32_16x16x32_bf16 v[50:53], v[34:37], v[46:49], v[54:57]
	v_mul_f32_e64 v42, v198, v190
	v_mul_f32_e64 v43, v199, v191
	v_pk_mul_f32 v[46:47], v[198:199], v[38:39]
	v_pk_fma_f32 v[42:43], v[74:75], v[38:39], v[42:43] neg_lo:[0,0,1] neg_hi:[0,0,1]
	v_mov_b32_e32 v56, v196
	s_waitcnt vmcnt(23)
	v_mov_b32_e32 v57, v194
	v_mov_b32_e32 v194, v197
	v_pk_fma_f32 v[54:55], v[74:75], v[190:191], v[46:47]
	v_pk_mul_f32 v[74:75], v[200:201], v[194:195]
	v_pk_mul_f32 v[78:79], v[200:201], v[56:57]
	v_pk_fma_f32 v[74:75], v[76:77], v[56:57], v[74:75] neg_lo:[0,0,1] neg_hi:[0,0,1]
	v_pk_fma_f32 v[76:77], v[76:77], v[194:195], v[78:79]
	v_pk_mul_f32 v[48:49], v[70:71], v[54:55]
	v_pk_mul_f32 v[80:81], v[72:73], v[76:77]
	v_pk_mul_f32 v[46:47], v[44:45], v[54:55]
	v_pk_fma_f32 v[48:49], v[44:45], v[42:43], v[48:49]
	v_pk_mul_f32 v[78:79], v[40:41], v[76:77]
	v_pk_fma_f32 v[80:81], v[40:41], v[74:75], v[80:81]
	v_pk_fma_f32 v[46:47], v[70:71], v[42:43], v[46:47] neg_lo:[0,0,1] neg_hi:[0,0,1]
	v_pk_fma_f32 v[78:79], v[72:73], v[74:75], v[78:79] neg_lo:[0,0,1] neg_hi:[0,0,1]
	v_cvt_pk_bf16_f32 v47, v47, v49
	v_cvt_pk_bf16_f32 v49, v79, v81
	v_cvt_pk_bf16_f32 v46, v46, v48
	v_cvt_pk_bf16_f32 v48, v78, v80
	s_nop 1
	v_mfma_f32_16x16x32_bf16 v[46:49], v[34:37], v[46:49], v[58:61]
	s_nop 2
	v_mul_f32_e64 v58, v190, v54
	v_mul_f32_e64 v59, v191, v55
	v_pk_mul_f32 v[54:55], v[38:39], v[54:55]
	v_pk_fma_f32 v[58:59], v[38:39], v[42:43], v[58:59] neg_lo:[0,0,1] neg_hi:[0,0,1]
	v_pk_fma_f32 v[42:43], v[190:191], v[42:43], v[54:55]
	s_nop 0
	v_pk_mul_f32 v[78:79], v[190:191], v[42:43]
	v_pk_mul_f32 v[54:55], v[44:45], v[42:43]
	v_pk_fma_f32 v[78:79], v[38:39], v[58:59], v[78:79] neg_lo:[0,0,1] neg_hi:[0,0,1]
	v_pk_mul_f32 v[38:39], v[38:39], v[42:43]
	v_pk_mul_f32 v[60:61], v[70:71], v[42:43]
	v_pk_fma_f32 v[38:39], v[190:191], v[58:59], v[38:39]
	v_pk_fma_f32 v[60:61], v[44:45], v[58:59], v[60:61]
	v_pk_mul_f32 v[42:43], v[44:45], v[38:39]
	v_pk_mul_f32 v[38:39], v[70:71], v[38:39]
	v_pk_fma_f32 v[54:55], v[70:71], v[58:59], v[54:55] neg_lo:[0,0,1] neg_hi:[0,0,1]
	v_pk_fma_f32 v[38:39], v[44:45], v[78:79], v[38:39]
	v_pk_mul_f32 v[44:45], v[56:57], v[76:77]
	v_pk_fma_f32 v[58:59], v[70:71], v[78:79], v[42:43] neg_lo:[0,0,1] neg_hi:[0,0,1]
	v_pk_mul_f32 v[42:43], v[194:195], v[76:77]
	v_pk_fma_f32 v[44:45], v[194:195], v[74:75], v[44:45]
	v_pk_fma_f32 v[42:43], v[56:57], v[74:75], v[42:43] neg_lo:[0,0,1] neg_hi:[0,0,1]
	v_pk_mul_f32 v[74:75], v[72:73], v[44:45]
	v_pk_mul_f32 v[70:71], v[40:41], v[44:45]
	v_pk_fma_f32 v[74:75], v[40:41], v[42:43], v[74:75]
	v_pk_mul_f32 v[76:77], v[194:195], v[44:45]
	v_pk_mul_f32 v[44:45], v[56:57], v[44:45]
	v_pk_fma_f32 v[70:71], v[72:73], v[42:43], v[70:71] neg_lo:[0,0,1] neg_hi:[0,0,1]
	v_pk_fma_f32 v[76:77], v[56:57], v[42:43], v[76:77] neg_lo:[0,0,1] neg_hi:[0,0,1]
	v_pk_fma_f32 v[56:57], v[194:195], v[42:43], v[44:45]
	v_cvt_pk_bf16_f32 v45, v71, v75
	v_cvt_pk_bf16_f32 v44, v70, v74
	v_cvt_pk_bf16_f32 v43, v55, v61
	v_cvt_pk_bf16_f32 v42, v54, v60
	v_pk_mul_f32 v[54:55], v[40:41], v[56:57]
	v_pk_mul_f32 v[56:57], v[72:73], v[56:57]
	v_pk_fma_f32 v[54:55], v[72:73], v[76:77], v[54:55] neg_lo:[0,0,1] neg_hi:[0,0,1]
	v_pk_fma_f32 v[40:41], v[40:41], v[76:77], v[56:57]
	v_cvt_pk_bf16_f32 v38, v58, v38
	v_cvt_pk_bf16_f32 v41, v55, v41
	v_cvt_pk_bf16_f32 v40, v54, v40
	v_cvt_pk_bf16_f32 v39, v59, v39
	s_waitcnt vmcnt(17)
	v_mov_b32_e32 v59, v182
	v_mov_b32_e32 v55, v32
	v_mov_b32_e32 v182, v185
	v_mov_b32_e32 v32, v31
	v_mov_b32_e32 v58, v184
	v_mov_b32_e32 v54, v30
	v_pk_mul_f32 v[30:31], v[182:183], v[32:33]
	v_mfma_f32_16x16x32_bf16 v[42:45], v[34:37], v[42:45], v[62:65]
	s_waitcnt vmcnt(13)
	v_mov_b32_e32 v57, v176
	v_mov_b32_e32 v176, v187
	v_mov_b32_e32 v56, v186
	v_mfma_f32_16x16x32_bf16 v[34:37], v[34:37], v[38:41], v[66:69]
	v_fma_f32 v38, v58, v54, -v30
	v_fma_f32 v39, v59, v55, -v31
	v_pk_mul_f32 v[30:31], v[182:183], v[54:55]
	s_nop 0
	v_pk_fma_f32 v[40:41], v[58:59], v[32:33], v[30:31]
	v_mov_b32_e32 v30, v22
	v_mov_b32_e32 v31, v24
	v_mov_b32_e32 v24, v23
	v_pk_mul_f32 v[60:61], v[176:177], v[30:31]
	v_pk_mul_f32 v[22:23], v[176:177], v[24:25]
	v_pk_fma_f32 v[60:61], v[56:57], v[24:25], v[60:61]
	v_pk_fma_f32 v[22:23], v[56:57], v[30:31], v[22:23] neg_lo:[0,0,1] neg_hi:[0,0,1]
	v_cvt_pk_bf16_f32 v39, v39, v41
	v_cvt_pk_bf16_f32 v41, v23, v61
	v_cvt_pk_bf16_f32 v38, v38, v40
	v_cvt_pk_bf16_f32 v40, v22, v60
	s_nop 1
	v_mfma_f32_16x16x32_bf16 v[38:41], v[14:17], v[38:41], v[50:53]
	s_nop 2
	v_mov_b32_e32 v51, v172
	v_mov_b32_e32 v172, v179
	v_mov_b32_e32 v50, v178
	v_pk_mul_f32 v[22:23], v[182:183], v[172:173]
	s_nop 0
	v_pk_fma_f32 v[52:53], v[58:59], v[50:51], v[22:23] neg_lo:[0,0,1] neg_hi:[0,0,1]
	v_pk_mul_f32 v[22:23], v[182:183], v[50:51]
	s_nop 0
	v_pk_fma_f32 v[58:59], v[58:59], v[172:173], v[22:23]
	s_nop 0
	v_pk_mul_f32 v[22:23], v[32:33], v[58:59]
	s_nop 0
	v_pk_fma_f32 v[60:61], v[54:55], v[52:53], v[22:23] neg_lo:[0,0,1] neg_hi:[0,0,1]
	v_pk_mul_f32 v[22:23], v[54:55], v[58:59]
	s_nop 0
	v_pk_fma_f32 v[62:63], v[32:33], v[52:53], v[22:23]
	v_mov_b32_e32 v22, v180
	s_waitcnt vmcnt(12)
	v_mov_b32_e32 v23, v170
	v_mov_b32_e32 v170, v181
	v_pk_mul_f32 v[64:65], v[176:177], v[170:171]
	v_pk_mul_f32 v[66:67], v[176:177], v[22:23]
	v_pk_fma_f32 v[64:65], v[56:57], v[22:23], v[64:65] neg_lo:[0,0,1] neg_hi:[0,0,1]
	v_pk_fma_f32 v[56:57], v[56:57], v[170:171], v[66:67]
	s_nop 0
	v_pk_mul_f32 v[68:69], v[30:31], v[56:57]
	v_pk_mul_f32 v[66:67], v[24:25], v[56:57]
	v_pk_fma_f32 v[68:69], v[24:25], v[64:65], v[68:69]
	v_pk_fma_f32 v[66:67], v[30:31], v[64:65], v[66:67] neg_lo:[0,0,1] neg_hi:[0,0,1]
	v_cvt_pk_bf16_f32 v61, v61, v63
	v_cvt_pk_bf16_f32 v63, v67, v69
	v_cvt_pk_bf16_f32 v60, v60, v62
	v_cvt_pk_bf16_f32 v62, v66, v68
	s_nop 1
	v_mfma_f32_16x16x32_bf16 v[46:49], v[14:17], v[60:63], v[46:49]
	v_mul_f32_e64 v60, v172, v58
	v_mul_f32_e64 v61, v173, v59
	v_pk_mul_f32 v[58:59], v[50:51], v[58:59]
	v_pk_fma_f32 v[60:61], v[50:51], v[52:53], v[60:61] neg_lo:[0,0,1] neg_hi:[0,0,1]
	v_pk_fma_f32 v[52:53], v[172:173], v[52:53], v[58:59]
	s_nop 0
	v_pk_mul_f32 v[66:67], v[172:173], v[52:53]
	v_pk_mul_f32 v[58:59], v[32:33], v[52:53]
	v_pk_fma_f32 v[66:67], v[50:51], v[60:61], v[66:67] neg_lo:[0,0,1] neg_hi:[0,0,1]
	v_pk_mul_f32 v[50:51], v[50:51], v[52:53]
	v_pk_mul_f32 v[62:63], v[54:55], v[52:53]
	v_pk_fma_f32 v[50:51], v[172:173], v[60:61], v[50:51]
	v_pk_fma_f32 v[58:59], v[54:55], v[60:61], v[58:59] neg_lo:[0,0,1] neg_hi:[0,0,1]
	v_pk_mul_f32 v[52:53], v[32:33], v[50:51]
	v_pk_fma_f32 v[62:63], v[32:33], v[60:61], v[62:63]
	v_pk_fma_f32 v[60:61], v[54:55], v[66:67], v[52:53] neg_lo:[0,0,1] neg_hi:[0,0,1]
	v_pk_mul_f32 v[50:51], v[54:55], v[50:51]
	v_pk_mul_f32 v[52:53], v[22:23], v[56:57]
	v_pk_fma_f32 v[32:33], v[32:33], v[66:67], v[50:51]
	v_pk_mul_f32 v[50:51], v[170:171], v[56:57]
	v_pk_fma_f32 v[52:53], v[170:171], v[64:65], v[52:53]
	v_pk_fma_f32 v[50:51], v[22:23], v[64:65], v[50:51] neg_lo:[0,0,1] neg_hi:[0,0,1]
	v_pk_mul_f32 v[56:57], v[30:31], v[52:53]
	v_pk_mul_f32 v[64:65], v[170:171], v[52:53]
	v_pk_mul_f32 v[54:55], v[24:25], v[52:53]
	v_pk_fma_f32 v[56:57], v[24:25], v[50:51], v[56:57]
	v_pk_fma_f32 v[64:65], v[22:23], v[50:51], v[64:65] neg_lo:[0,0,1] neg_hi:[0,0,1]
	v_pk_mul_f32 v[22:23], v[22:23], v[52:53]
	v_pk_fma_f32 v[54:55], v[30:31], v[50:51], v[54:55] neg_lo:[0,0,1] neg_hi:[0,0,1]
	v_pk_fma_f32 v[22:23], v[170:171], v[50:51], v[22:23]
	v_cvt_pk_bf16_f32 v53, v55, v57
	v_cvt_pk_bf16_f32 v52, v54, v56
	v_cvt_pk_bf16_f32 v51, v59, v63
	v_cvt_pk_bf16_f32 v50, v58, v62
	s_nop 1
	v_mfma_f32_16x16x32_bf16 v[42:45], v[14:17], v[50:53], v[42:45]
	v_mul_f32_e64 v50, v24, v22
	v_mul_f32_e64 v51, v25, v23
	v_pk_mul_f32 v[22:23], v[30:31], v[22:23]
	v_pk_fma_f32 v[50:51], v[30:31], v[64:65], v[50:51] neg_lo:[0,0,1] neg_hi:[0,0,1]
	v_pk_fma_f32 v[22:23], v[24:25], v[64:65], v[22:23]
	s_nop 0
	v_cvt_pk_bf16_f32 v25, v51, v23
	v_cvt_pk_bf16_f32 v23, v61, v33
	v_cvt_pk_bf16_f32 v24, v50, v22
	v_cvt_pk_bf16_f32 v22, v60, v32
	s_waitcnt vmcnt(7)
	v_mov_b32_e32 v50, v26
	v_mov_b32_e32 v51, v28
	v_mfma_f32_16x16x32_bf16 v[34:37], v[14:17], v[22:25], v[34:37]
	s_waitcnt vmcnt(6)
	v_mov_b32_e32 v23, v164
	v_mov_b32_e32 v164, v163
	v_mov_b32_e32 v28, v27
	s_waitcnt vmcnt(4)
	v_mov_b32_e32 v25, v174
	v_mov_b32_e32 v26, v18
	v_mov_b32_e32 v27, v20
	s_waitcnt vmcnt(3)
	v_mov_b32_e32 v174, v169
	v_mov_b32_e32 v22, v162
	v_pk_mul_f32 v[16:17], v[164:165], v[50:51]
	v_mov_b32_e32 v24, v168
	v_mov_b32_e32 v20, v19
	v_pk_mul_f32 v[30:31], v[174:175], v[26:27]
	v_pk_mul_f32 v[14:15], v[164:165], v[28:29]
	v_pk_fma_f32 v[16:17], v[22:23], v[28:29], v[16:17]
	v_pk_mul_f32 v[18:19], v[174:175], v[20:21]
	v_pk_fma_f32 v[30:31], v[24:25], v[20:21], v[30:31]
	v_pk_fma_f32 v[14:15], v[22:23], v[50:51], v[14:15] neg_lo:[0,0,1] neg_hi:[0,0,1]
	v_pk_fma_f32 v[18:19], v[24:25], v[26:27], v[18:19] neg_lo:[0,0,1] neg_hi:[0,0,1]
	v_cvt_pk_bf16_f32 v15, v15, v17
	v_cvt_pk_bf16_f32 v17, v19, v31
	v_cvt_pk_bf16_f32 v14, v14, v16
	v_cvt_pk_bf16_f32 v16, v18, v30
	v_mov_b32_e32 v19, v158
	v_mov_b32_e32 v158, v161
	v_mfma_f32_16x16x32_bf16 v[30:33], v[10:13], v[14:17], v[38:41]
	v_mov_b32_e32 v18, v160
	v_pk_mul_f32 v[14:15], v[164:165], v[158:159]
	s_waitcnt vmcnt(1)
	v_mov_b32_e32 v53, v188
	v_pk_fma_f32 v[38:39], v[22:23], v[18:19], v[14:15] neg_lo:[0,0,1] neg_hi:[0,0,1]
	v_pk_mul_f32 v[14:15], v[164:165], v[18:19]
	v_mov_b32_e32 v188, v167
	v_pk_fma_f32 v[40:41], v[22:23], v[158:159], v[14:15]
	v_mov_b32_e32 v52, v166
	v_pk_mul_f32 v[22:23], v[174:175], v[188:189]
	v_pk_mul_f32 v[16:17], v[50:51], v[40:41]
	v_pk_fma_f32 v[54:55], v[24:25], v[52:53], v[22:23] neg_lo:[0,0,1] neg_hi:[0,0,1]
	v_pk_mul_f32 v[22:23], v[174:175], v[52:53]
	v_pk_mul_f32 v[14:15], v[28:29], v[40:41]
	v_pk_fma_f32 v[56:57], v[24:25], v[188:189], v[22:23]
	v_pk_fma_f32 v[16:17], v[28:29], v[38:39], v[16:17]
	v_pk_mul_f32 v[24:25], v[26:27], v[56:57]
	v_pk_mul_f32 v[22:23], v[20:21], v[56:57]
	v_pk_fma_f32 v[24:25], v[20:21], v[54:55], v[24:25]
	v_pk_fma_f32 v[14:15], v[50:51], v[38:39], v[14:15] neg_lo:[0,0,1] neg_hi:[0,0,1]
	v_pk_fma_f32 v[22:23], v[26:27], v[54:55], v[22:23] neg_lo:[0,0,1] neg_hi:[0,0,1]
	v_cvt_pk_bf16_f32 v15, v15, v17
	v_cvt_pk_bf16_f32 v17, v23, v25
	v_cvt_pk_bf16_f32 v14, v14, v16
	v_cvt_pk_bf16_f32 v16, v22, v24
	s_nop 1
	v_mfma_f32_16x16x32_bf16 v[22:25], v[10:13], v[14:17], v[46:49]
	v_mul_f32_e64 v16, v18, v40
	v_mul_f32_e64 v17, v19, v41
	v_pk_mul_f32 v[14:15], v[158:159], v[40:41]
	v_pk_fma_f32 v[16:17], v[158:159], v[38:39], v[16:17]
	v_pk_fma_f32 v[14:15], v[18:19], v[38:39], v[14:15] neg_lo:[0,0,1] neg_hi:[0,0,1]
	v_pk_mul_f32 v[38:39], v[28:29], v[16:17]
	v_pk_mul_f32 v[40:41], v[50:51], v[16:17]
	v_pk_mul_f32 v[46:47], v[158:159], v[16:17]
	v_pk_mul_f32 v[16:17], v[18:19], v[16:17]
	v_pk_fma_f32 v[38:39], v[50:51], v[14:15], v[38:39] neg_lo:[0,0,1] neg_hi:[0,0,1]
	v_pk_fma_f32 v[40:41], v[28:29], v[14:15], v[40:41]
	v_pk_fma_f32 v[46:47], v[18:19], v[14:15], v[46:47] neg_lo:[0,0,1] neg_hi:[0,0,1]
	v_pk_fma_f32 v[14:15], v[158:159], v[14:15], v[16:17]
	s_nop 0
	v_pk_mul_f32 v[16:17], v[28:29], v[14:15]
	v_pk_mul_f32 v[14:15], v[50:51], v[14:15]
	v_pk_fma_f32 v[18:19], v[50:51], v[46:47], v[16:17] neg_lo:[0,0,1] neg_hi:[0,0,1]
	v_pk_mul_f32 v[16:17], v[52:53], v[56:57]
	v_pk_fma_f32 v[28:29], v[28:29], v[46:47], v[14:15]
	v_pk_mul_f32 v[14:15], v[188:189], v[56:57]
	v_pk_fma_f32 v[16:17], v[188:189], v[54:55], v[16:17]
	v_pk_fma_f32 v[14:15], v[52:53], v[54:55], v[14:15] neg_lo:[0,0,1] neg_hi:[0,0,1]
	v_pk_mul_f32 v[48:49], v[26:27], v[16:17]
	v_pk_mul_f32 v[46:47], v[20:21], v[16:17]
	v_pk_fma_f32 v[48:49], v[20:21], v[14:15], v[48:49]
	v_pk_mul_f32 v[50:51], v[188:189], v[16:17]
	v_pk_mul_f32 v[16:17], v[52:53], v[16:17]
	v_pk_fma_f32 v[46:47], v[26:27], v[14:15], v[46:47] neg_lo:[0,0,1] neg_hi:[0,0,1]
	v_pk_fma_f32 v[50:51], v[52:53], v[14:15], v[50:51] neg_lo:[0,0,1] neg_hi:[0,0,1]
	v_pk_fma_f32 v[52:53], v[188:189], v[14:15], v[16:17]
	v_cvt_pk_bf16_f32 v17, v47, v49
	v_cvt_pk_bf16_f32 v16, v46, v48
	v_cvt_pk_bf16_f32 v15, v39, v41
	v_cvt_pk_bf16_f32 v14, v38, v40
	v_pk_mul_f32 v[38:39], v[20:21], v[52:53]
	s_nop 0
	v_pk_fma_f32 v[38:39], v[26:27], v[50:51], v[38:39] neg_lo:[0,0,1] neg_hi:[0,0,1]
	v_pk_mul_f32 v[26:27], v[26:27], v[52:53]
	s_nop 0
	v_pk_fma_f32 v[20:21], v[20:21], v[50:51], v[26:27]
	v_cvt_pk_bf16_f32 v19, v19, v29
	v_cvt_pk_bf16_f32 v18, v18, v28
	v_cvt_pk_bf16_f32 v21, v39, v21
	v_cvt_pk_bf16_f32 v20, v38, v20
	v_mfma_f32_16x16x32_bf16 v[14:17], v[10:13], v[14:17], v[42:45]
	v_mov_b32_e32 v29, v32
	v_mov_b32_e32 v32, v31
	v_mov_b32_e32 v28, v30
	v_mfma_f32_16x16x32_bf16 v[10:13], v[10:13], v[18:21], v[34:37]
	s_waitcnt vmcnt(0)
	v_mov_b32_e32 v19, v8
	v_mov_b32_e32 v8, v7
	v_mov_b32_e32 v18, v6
	v_add_u32_e32 v34, s22, v242
	ds_read_b64 v[20:21], v34
	v_add_u32_e32 v242, 32, v242
	s_waitcnt lgkmcnt(0)
	v_lshlrev_b32_e32 v27, 16, v21
	v_lshlrev_b32_e32 v26, 16, v20
	v_and_b32_e32 v21, 0xffff0000, v21
	v_and_b32_e32 v20, 0xffff0000, v20
	v_pk_fma_f32 v[20:21], v[8:9], v[20:21], v[32:33]
	v_pk_fma_f32 v[26:27], v[18:19], v[26:27], v[28:29]
	v_mul_f32_e32 v7, 0x3d372713, v20
	v_mul_f32_e32 v7, v20, v7
	v_fma_f32 v7, v20, v7, v20
	v_mul_f32_e32 v7, 0x3f4c422a, v7
	v_mul_f32_e32 v7, -2.0, v7
	v_mul_f32_e32 v7, 0x3fb8aa3b, v7
	v_exp_f32_e32 v7, v7
	v_mul_f32_e32 v6, 0x3d372713, v26
	v_mul_f32_e32 v6, v26, v6
	v_fma_f32 v6, v26, v6, v26
	v_add_f32_e32 v7, 1.0, v7
	v_rcp_f32_e32 v28, v7
	v_mul_f32_e32 v7, 0x3d372713, v27
	v_mul_f32_e32 v7, v27, v7
	v_fma_f32 v7, v27, v7, v27
	v_mul_f32_e32 v6, 0x3f4c422a, v6
	v_mul_f32_e32 v7, 0x3f4c422a, v7
	v_mul_f32_e32 v6, -2.0, v6
	v_mul_f32_e32 v7, -2.0, v7
	v_mul_f32_e32 v6, 0x3fb8aa3b, v6
	v_mul_f32_e32 v7, 0x3fb8aa3b, v7
	v_exp_f32_e32 v6, v6
	v_exp_f32_e32 v7, v7
	v_add_f32_e32 v6, 1.0, v6
	v_add_f32_e32 v7, 1.0, v7
	v_rcp_f32_e32 v6, v6
	v_rcp_f32_e32 v7, v7
	s_nop 0
	v_pk_mul_f32 v[6:7], v[26:27], v[6:7]
	v_mul_f32_e32 v26, 0x3d372713, v21
	v_mul_f32_e32 v26, v21, v26
	v_fma_f32 v26, v21, v26, v21
	v_mul_f32_e32 v26, 0x3f4c422a, v26
	v_mul_f32_e32 v26, -2.0, v26
	v_mul_f32_e32 v26, 0x3fb8aa3b, v26
	v_exp_f32_e32 v26, v26
	s_nop 0
	v_add_f32_e32 v26, 1.0, v26
	v_rcp_f32_e32 v29, v26
	s_nop 0
	v_pk_mul_f32 v[20:21], v[20:21], v[28:29]
	s_nop 0
	v_cvt_pk_bf16_f32 v6, v6, v20
	v_cvt_pk_bf16_f32 v7, v7, v21
	ds_write_b64 v34, v[6:7]
	v_add_u32_e32 v28, s22, v241
	ds_read_b64 v[6:7], v28 offset:33280
	v_mov_b32_e32 v27, v24
	v_mov_b32_e32 v24, v23
	v_mov_b32_e32 v26, v22
	v_add_u32_e32 v241, 32, v241
	s_waitcnt lgkmcnt(0)
	v_lshlrev_b32_e32 v21, 16, v7
	v_lshlrev_b32_e32 v20, 16, v6
	v_and_b32_e32 v7, 0xffff0000, v7
	v_and_b32_e32 v6, 0xffff0000, v6
	v_pk_fma_f32 v[6:7], v[8:9], v[6:7], v[24:25]
	v_pk_fma_f32 v[20:21], v[18:19], v[20:21], v[26:27]
	v_mul_f32_e32 v23, 0x3d372713, v6
	v_mul_f32_e32 v23, v6, v23
	v_fma_f32 v23, v6, v23, v6
	v_mul_f32_e32 v23, 0x3f4c422a, v23
	v_mul_f32_e32 v23, -2.0, v23
	v_mul_f32_e32 v23, 0x3fb8aa3b, v23
	v_exp_f32_e32 v23, v23
	v_mul_f32_e32 v22, 0x3d372713, v20
	v_mul_f32_e32 v22, v20, v22
	v_fma_f32 v22, v20, v22, v20
	v_add_f32_e32 v23, 1.0, v23
	v_rcp_f32_e32 v24, v23
	v_mul_f32_e32 v23, 0x3d372713, v21
	v_mul_f32_e32 v23, v21, v23
	v_fma_f32 v23, v21, v23, v21
	v_mul_f32_e32 v22, 0x3f4c422a, v22
	v_mul_f32_e32 v23, 0x3f4c422a, v23
	v_mul_f32_e32 v22, -2.0, v22
	v_mul_f32_e32 v23, -2.0, v23
	v_mul_f32_e32 v22, 0x3fb8aa3b, v22
	v_mul_f32_e32 v23, 0x3fb8aa3b, v23
	v_exp_f32_e32 v22, v22
	v_exp_f32_e32 v23, v23
	v_add_f32_e32 v22, 1.0, v22
	v_add_f32_e32 v23, 1.0, v23
	v_rcp_f32_e32 v22, v22
	v_rcp_f32_e32 v23, v23
	s_nop 0
	v_pk_mul_f32 v[20:21], v[20:21], v[22:23]
	v_mul_f32_e32 v22, 0x3d372713, v7
	v_mul_f32_e32 v22, v7, v22
	v_fma_f32 v22, v7, v22, v7
	v_mul_f32_e32 v22, 0x3f4c422a, v22
	v_mul_f32_e32 v22, -2.0, v22
	v_mul_f32_e32 v22, 0x3fb8aa3b, v22
	v_exp_f32_e32 v22, v22
	s_nop 0
	v_add_f32_e32 v22, 1.0, v22
	v_rcp_f32_e32 v25, v22
	s_nop 0
	v_pk_mul_f32 v[6:7], v[6:7], v[24:25]
	s_nop 0
	v_cvt_pk_bf16_f32 v6, v20, v6
	v_cvt_pk_bf16_f32 v7, v21, v7
	ds_write_b64 v28, v[6:7] offset:33280
	ds_read_b64 v[6:7], v28 offset:49920
	v_mov_b32_e32 v23, v16
	v_mov_b32_e32 v16, v15
	v_mov_b32_e32 v22, v14
	s_waitcnt lgkmcnt(0)
	v_lshlrev_b32_e32 v21, 16, v7
	v_lshlrev_b32_e32 v20, 16, v6
	v_and_b32_e32 v7, 0xffff0000, v7
	v_and_b32_e32 v6, 0xffff0000, v6
	v_pk_fma_f32 v[6:7], v[8:9], v[6:7], v[16:17]
	v_pk_fma_f32 v[20:21], v[18:19], v[20:21], v[22:23]
	v_mul_f32_e32 v15, 0x3d372713, v6
	v_mul_f32_e32 v15, v6, v15
	v_fma_f32 v15, v6, v15, v6
	v_mul_f32_e32 v15, 0x3f4c422a, v15
	v_mul_f32_e32 v15, -2.0, v15
	v_mul_f32_e32 v15, 0x3fb8aa3b, v15
	v_exp_f32_e32 v15, v15
	v_mul_f32_e32 v14, 0x3d372713, v20
	v_mul_f32_e32 v14, v20, v14
	v_mul_f32_e32 v17, 0x3d372713, v7
	v_add_f32_e32 v15, 1.0, v15
	v_rcp_f32_e32 v16, v15
	v_mul_f32_e32 v15, 0x3d372713, v21
	v_mul_f32_e32 v15, v21, v15
	v_fma_f32 v14, v20, v14, v20
	v_fma_f32 v15, v21, v15, v21
	v_mul_f32_e32 v17, v7, v17
	v_mul_f32_e32 v14, 0x3f4c422a, v14
	v_mul_f32_e32 v15, 0x3f4c422a, v15
	v_fma_f32 v17, v7, v17, v7
	v_mul_f32_e32 v14, -2.0, v14
	v_mul_f32_e32 v15, -2.0, v15
	v_mul_f32_e32 v17, 0x3f4c422a, v17
	v_mul_f32_e32 v14, 0x3fb8aa3b, v14
	v_mul_f32_e32 v15, 0x3fb8aa3b, v15
	v_mul_f32_e32 v17, -2.0, v17
	v_exp_f32_e32 v14, v14
	v_exp_f32_e32 v15, v15
	v_mul_f32_e32 v17, 0x3fb8aa3b, v17
	v_exp_f32_e32 v17, v17
	v_add_f32_e32 v14, 1.0, v14
	v_add_f32_e32 v15, 1.0, v15
	v_rcp_f32_e32 v14, v14
	v_rcp_f32_e32 v15, v15
	v_add_f32_e32 v17, 1.0, v17
	v_rcp_f32_e32 v17, v17
	v_pk_mul_f32 v[14:15], v[20:21], v[14:15]
	v_add_u32_e32 v20, 0x10400, v28
	v_pk_mul_f32 v[6:7], v[6:7], v[16:17]
	s_nop 0
	v_cvt_pk_bf16_f32 v7, v15, v7
	v_cvt_pk_bf16_f32 v6, v14, v6
	ds_write_b64 v28, v[6:7] offset:49920
	ds_read_b64 v[6:7], v20
	v_mov_b32_e32 v16, v10
	v_mov_b32_e32 v17, v12
	v_mov_b32_e32 v12, v11
	s_waitcnt lgkmcnt(0)
	v_lshlrev_b32_e32 v15, 16, v7
	v_lshlrev_b32_e32 v14, 16, v6
	v_pk_fma_f32 v[14:15], v[18:19], v[14:15], v[16:17]
	v_and_b32_e32 v7, 0xffff0000, v7
	v_and_b32_e32 v6, 0xffff0000, v6
	v_pk_fma_f32 v[6:7], v[8:9], v[6:7], v[12:13]
	v_mul_f32_e32 v9, 0x3d372713, v15
	v_mul_f32_e32 v9, v15, v9
	v_fma_f32 v9, v15, v9, v15
	v_mul_f32_e32 v9, 0x3f4c422a, v9
	v_mul_f32_e32 v9, -2.0, v9
	v_mul_f32_e32 v9, 0x3fb8aa3b, v9
	v_exp_f32_e32 v9, v9
	v_mul_f32_e32 v10, 0x3d372713, v14
	v_mul_f32_e32 v10, v14, v10
	v_mul_f32_e32 v8, 0x3d372713, v6
	v_add_f32_e32 v9, 1.0, v9
	v_rcp_f32_e32 v11, v9
	v_mul_f32_e32 v9, 0x3d372713, v7
	v_fma_f32 v10, v14, v10, v14
	v_mul_f32_e32 v8, v6, v8
	v_mul_f32_e32 v9, v7, v9
	v_mul_f32_e32 v10, 0x3f4c422a, v10
	v_fma_f32 v8, v6, v8, v6
	v_fma_f32 v9, v7, v9, v7
	v_mul_f32_e32 v10, -2.0, v10
	v_mul_f32_e32 v8, 0x3f4c422a, v8
	v_mul_f32_e32 v9, 0x3f4c422a, v9
	v_mul_f32_e32 v10, 0x3fb8aa3b, v10
	v_mul_f32_e32 v8, -2.0, v8
	v_mul_f32_e32 v9, -2.0, v9
	v_exp_f32_e32 v10, v10
	v_mul_f32_e32 v8, 0x3fb8aa3b, v8
	v_mul_f32_e32 v9, 0x3fb8aa3b, v9
	v_exp_f32_e32 v8, v8
	v_exp_f32_e32 v9, v9
	v_add_f32_e32 v10, 1.0, v10
	v_rcp_f32_e32 v10, v10
	v_add_f32_e32 v8, 1.0, v8
	v_add_f32_e32 v9, 1.0, v9
	v_rcp_f32_e32 v8, v8
	v_rcp_f32_e32 v9, v9
	v_pk_mul_f32 v[10:11], v[14:15], v[10:11]
	v_pk_mul_f32 v[6:7], v[6:7], v[8:9]
	s_nop 0
	v_cvt_pk_bf16_f32 v7, v11, v7
	v_cvt_pk_bf16_f32 v6, v10, v6
	ds_write_b64 v20, v[6:7]
	s_cbranch_scc0 .LBB0_464
	s_and_b32 s0, s20, 0xffffffc0
	v_or_b32_e32 v6, s0, v1
	v_ashrrev_i32_e32 v7, 31, v6
	v_readlane_b32 s4, v254, 8
	v_lshlrev_b64 v[10:11], 10, v[6:7]
	v_readlane_b32 s5, v254, 9
	s_ashr_i32 s1, s0, 31
	v_readlane_b32 s6, v254, 10
	v_lshl_add_u64 v[6:7], s[4:5], 0, v[10:11]
	s_nop 1
	s_mov_b64 s[36:37], s[4:5]
	s_add_u32 s38, s4, 0x4000
	s_addc_u32 s39, s5, 0
	s_add_u32 s40, s4, 0x8000
	s_addc_u32 s41, s5, 0
	s_add_u32 s44, s4, 0xc000
	s_addc_u32 s45, s5, 0
	s_lshl_b64 s[4:5], s[0:1], 2
	s_add_u32 s4, s6, s4
	v_readlane_b32 s6, v254, 11
	s_addc_u32 s5, s6, s5
	v_readlane_b32 s6, v251, 55
	v_lshlrev_b32_e32 v12, 1, v238
	v_lshlrev_b32_e32 v239, 6, v1
	s_lshl_b32 s48, s0, 10
	v_add3_u32 v239, v239, v12, s48
	v_mov_b32_e32 v13, v139
	v_readlane_b32 s7, v251, 56
	v_lshl_add_u64 v[136:137], v[6:7], 0, v[12:13]
	v_or_b32_e32 v22, s88, v1
	v_mov_b64_e32 v[6:7], s[6:7]
	s_movk_i32 s10, 0x2800
	v_mad_i64_i32 v[134:135], s[6:7], v22, s10, v[6:7]
	s_lshl_b64 s[6:7], s[0:1], 1
	s_nop 0
	v_lshl_add_u64 v[8:9], v[134:135], 0, s[6:7]
	v_lshlrev_b32_e32 v14, 1, v146
	v_mov_b32_e32 v15, v139
	v_lshl_add_u64 v[16:17], v[8:9], 0, v[14:15]
	v_or_b32_e32 v8, 16, v22
	v_mad_i64_i32 v[8:9], s[8:9], v8, s10, v[6:7]
	v_lshl_add_u64 v[8:9], v[8:9], 0, s[6:7]
	v_lshl_add_u64 v[18:19], v[8:9], 0, v[14:15]
	v_or_b32_e32 v8, 32, v22
	v_mad_i64_i32 v[8:9], s[8:9], v8, s10, v[6:7]
	v_lshl_add_u64 v[8:9], v[8:9], 0, s[6:7]
	v_lshl_add_u64 v[20:21], v[8:9], 0, v[14:15]
	v_or_b32_e32 v8, 48, v22
	v_mad_i64_i32 v[6:7], s[8:9], v8, s10, v[6:7]
	v_lshl_add_u64 v[6:7], v[6:7], 0, s[6:7]
	v_lshl_add_u64 v[14:15], v[6:7], 0, v[14:15]
	v_add_co_u32_e32 v6, vcc, s69, v136
	v_lshlrev_b32_e32 v13, 2, v146
	s_nop 0
	v_addc_co_u32_e32 v7, vcc, 0, v137, vcc
	v_add_co_u32_e32 v8, vcc, s19, v136
	s_nop 0
	s_nop 0
	v_addc_co_u32_e32 v9, vcc, 0, v137, vcc
	s_nop 0
	s_nop 0
	s_nop 0
	s_nop 0
	v_add_co_u32_e32 v6, vcc, s27, v136
	v_add_u32_e32 v150, 0, v237
	s_nop 0
	v_addc_co_u32_e32 v7, vcc, 0, v137, vcc
	s_nop 0
	s_nop 0
	s_nop 0
	s_nop 0
	v_lshlrev_b32_e32 v220, 2, v146
	s_mov_b64 s[46:47], s[4:5]
	v_add_u32_e32 v221, 0x1000, v239
	v_add_u32_e32 v237, 0x2000, v239
	v_add_u32_e32 v238, 0x3000, v239
	global_load_dwordx4 v[74:77], v239, s[36:37] offset:0
	global_load_dwordx4 v[140:143], v239, s[36:37] offset:1024
	global_load_dwordx4 v[96:99], v239, s[38:39] offset:0
	global_load_dwordx4 v[152:155], v239, s[38:39] offset:1024
	global_load_dwordx4 v[92:95], v239, s[40:41] offset:0
	global_load_dwordx4 v[156:159], v239, s[40:41] offset:1024
	global_load_dwordx4 v[88:91], v239, s[44:45] offset:0
	global_load_dwordx4 v[160:163], v239, s[44:45] offset:1024
	global_load_dwordx4 v[180:183], v239, s[36:37] offset:2048
	global_load_dwordx4 v[196:199], v239, s[36:37] offset:3072
	global_load_dwordx4 v[184:187], v239, s[38:39] offset:2048
	global_load_dwordx4 v[200:203], v239, s[38:39] offset:3072
	global_load_dwordx4 v[188:191], v239, s[40:41] offset:2048
	global_load_dwordx4 v[204:207], v239, s[40:41] offset:3072
	global_load_dwordx4 v[192:195], v239, s[44:45] offset:2048
	global_load_dwordx4 v[208:211], v239, s[44:45] offset:3072
	global_load_dwordx4 v[212:215], v221, s[36:37] offset:0
	global_load_dwordx4 v[66:69], v221, s[36:37] offset:1024
	global_load_dwordx4 v[216:219], v221, s[38:39] offset:0
	global_load_dwordx4 v[46:49], v221, s[38:39] offset:1024
	global_load_dwordx4 v[240:243], v221, s[40:41] offset:0
	global_load_dwordx4 v[26:29], v221, s[40:41] offset:1024
	global_load_dwordx4 v[244:247], v221, s[44:45] offset:0
	global_load_dwordx4 v[6:9], v221, s[44:45] offset:1024
	global_load_dwordx2 v[78:79], v[16:17], off offset:2560
	global_load_dwordx2 v[126:127], v[16:17], off offset:2592
	global_load_dwordx2 v[118:119], v[16:17], off offset:2624
	global_load_dwordx2 v[110:111], v[16:17], off offset:2656
	global_load_dwordx2 v[132:133], v[18:19], off offset:2560
	global_load_dwordx2 v[124:125], v[18:19], off offset:2592
	global_load_dwordx2 v[116:117], v[18:19], off offset:2624
	global_load_dwordx2 v[108:109], v[18:19], off offset:2656
	global_load_dwordx2 v[130:131], v[20:21], off offset:2560
	global_load_dwordx2 v[122:123], v[20:21], off offset:2592
	global_load_dwordx2 v[114:115], v[20:21], off offset:2624
	global_load_dwordx2 v[106:107], v[20:21], off offset:2656
	global_load_dwordx2 v[128:129], v[14:15], off offset:2560
	global_load_dwordx2 v[120:121], v[14:15], off offset:2592
	global_load_dwordx2 v[112:113], v[14:15], off offset:2624
	global_load_dwordx2 v[104:105], v[14:15], off offset:2656
	v_readlane_b32 s4, v254, 61
	v_or_b32_e32 v10, v10, v138
	v_readlane_b32 s5, v254, 62
	v_mov_b32_e32 v30, 0
	v_add_u32_e32 v151, v150, v12
	v_lshl_add_u64 v[148:149], s[4:5], 0, v[10:11]
	s_mov_b64 s[22:23], 0
	s_mov_b32 s1, 64
	v_mov_b32_e32 v31, v30
	v_mov_b32_e32 v32, v30
	v_mov_b32_e32 v33, v30
	v_mov_b32_e32 v34, v30
	v_mov_b32_e32 v35, v30
	v_mov_b32_e32 v36, v30
	v_mov_b32_e32 v37, v30
	v_mov_b32_e32 v38, v30
	v_mov_b32_e32 v39, v30
	v_mov_b32_e32 v40, v30
	v_mov_b32_e32 v41, v30
	v_mov_b32_e32 v42, v30
	v_mov_b32_e32 v43, v30
	v_mov_b32_e32 v44, v30
	v_mov_b32_e32 v45, v30
	v_mov_b32_e32 v50, v30
	v_mov_b32_e32 v51, v30
	v_mov_b32_e32 v52, v30
	v_mov_b32_e32 v53, v30
	v_mov_b32_e32 v54, v30
	v_mov_b32_e32 v55, v30
	v_mov_b32_e32 v56, v30
	v_mov_b32_e32 v57, v30
	v_mov_b32_e32 v58, v30
	v_mov_b32_e32 v59, v30
	v_mov_b32_e32 v60, v30
	v_mov_b32_e32 v61, v30
	v_mov_b32_e32 v62, v30
	v_mov_b32_e32 v63, v30
	v_mov_b32_e32 v64, v30
	v_mov_b32_e32 v65, v30
	v_mov_b32_e32 v70, v30
	v_mov_b32_e32 v71, v30
	v_mov_b32_e32 v72, v30
	v_mov_b32_e32 v73, v30
	v_mov_b32_e32 v84, v30
	v_mov_b32_e32 v85, v30
	v_mov_b32_e32 v86, v30
	v_mov_b32_e32 v87, v30
	v_mov_b32_e32 v80, v30
	v_mov_b32_e32 v81, v30
	v_mov_b32_e32 v82, v30
	v_mov_b32_e32 v83, v30
	v_mov_b32_e32 v100, v30
	v_mov_b32_e32 v101, v30
	v_mov_b32_e32 v102, v30
	v_mov_b32_e32 v103, v30
	v_mov_b32_e32 v22, v30
	v_mov_b32_e32 v23, v30
	v_mov_b32_e32 v24, v30
	v_mov_b32_e32 v25, v30
	v_mov_b32_e32 v18, v30
	v_mov_b32_e32 v19, v30
	v_mov_b32_e32 v20, v30
	v_mov_b32_e32 v21, v30
	v_mov_b32_e32 v14, v30
	v_mov_b32_e32 v15, v30
	v_mov_b32_e32 v16, v30
	v_mov_b32_e32 v17, v30
	v_mov_b32_e32 v10, v30
	v_mov_b32_e32 v11, v30
	v_mov_b32_e32 v12, v30
	v_mov_b32_e32 v13, v30
	s_waitcnt lgkmcnt(0)
	s_barrier
.LBB0_466:
	v_add_u32_e32 v138, 0x10400, v151
	ds_read_b128 v[164:167], v151 offset:16640
	ds_read_b128 v[172:175], v151 offset:33280
	ds_read_b128 v[168:171], v151 offset:49920
	ds_read_b128 v[176:179], v138 offset:0
	s_waitcnt vmcnt(33)
	s_waitcnt lgkmcnt(3)
	v_mfma_f32_16x16x32_bf16 v[100:103], v[74:77], v[164:167], v[100:103]
	v_mfma_f32_16x16x32_bf16 v[62:65], v[96:99], v[164:167], v[62:65]
	v_mfma_f32_16x16x32_bf16 v[42:45], v[92:95], v[164:167], v[42:45]
	v_mfma_f32_16x16x32_bf16 v[22:25], v[88:91], v[164:167], v[22:25]
	ds_read_b128 v[164:167], v151 offset:16704
	s_waitcnt lgkmcnt(3)
	v_mfma_f32_16x16x32_bf16 v[80:83], v[74:77], v[172:175], v[80:83]
	v_mfma_f32_16x16x32_bf16 v[58:61], v[96:99], v[172:175], v[58:61]
	v_mfma_f32_16x16x32_bf16 v[38:41], v[92:95], v[172:175], v[38:41]
	v_mfma_f32_16x16x32_bf16 v[18:21], v[88:91], v[172:175], v[18:21]
	ds_read_b128 v[172:175], v151 offset:33344
	s_waitcnt lgkmcnt(3)
	v_mfma_f32_16x16x32_bf16 v[84:87], v[74:77], v[168:171], v[84:87]
	v_mfma_f32_16x16x32_bf16 v[54:57], v[96:99], v[168:171], v[54:57]
	v_mfma_f32_16x16x32_bf16 v[34:37], v[92:95], v[168:171], v[34:37]
	v_mfma_f32_16x16x32_bf16 v[14:17], v[88:91], v[168:171], v[14:17]
	ds_read_b128 v[168:171], v151 offset:49984
	s_waitcnt lgkmcnt(3)
	v_mfma_f32_16x16x32_bf16 v[70:73], v[74:77], v[176:179], v[70:73]
	v_mfma_f32_16x16x32_bf16 v[50:53], v[96:99], v[176:179], v[50:53]
	v_mfma_f32_16x16x32_bf16 v[30:33], v[92:95], v[176:179], v[30:33]
	v_mfma_f32_16x16x32_bf16 v[10:13], v[88:91], v[176:179], v[10:13]
	ds_read_b128 v[176:179], v138 offset:64
	s_waitcnt vmcnt(32)
	s_waitcnt lgkmcnt(3)
	v_mfma_f32_16x16x32_bf16 v[100:103], v[140:143], v[164:167], v[100:103]
	v_mfma_f32_16x16x32_bf16 v[62:65], v[152:155], v[164:167], v[62:65]
	v_mfma_f32_16x16x32_bf16 v[42:45], v[156:159], v[164:167], v[42:45]
	v_mfma_f32_16x16x32_bf16 v[22:25], v[160:163], v[164:167], v[22:25]
	ds_read_b128 v[164:167], v151 offset:16768
	s_waitcnt lgkmcnt(3)
	v_mfma_f32_16x16x32_bf16 v[80:83], v[140:143], v[172:175], v[80:83]
	v_mfma_f32_16x16x32_bf16 v[58:61], v[152:155], v[172:175], v[58:61]
	v_mfma_f32_16x16x32_bf16 v[38:41], v[156:159], v[172:175], v[38:41]
	v_mfma_f32_16x16x32_bf16 v[18:21], v[160:163], v[172:175], v[18:21]
	ds_read_b128 v[172:175], v151 offset:33408
	s_waitcnt lgkmcnt(3)
	v_mfma_f32_16x16x32_bf16 v[84:87], v[140:143], v[168:171], v[84:87]
	v_mfma_f32_16x16x32_bf16 v[54:57], v[152:155], v[168:171], v[54:57]
	v_mfma_f32_16x16x32_bf16 v[34:37], v[156:159], v[168:171], v[34:37]
	v_mfma_f32_16x16x32_bf16 v[14:17], v[160:163], v[168:171], v[14:17]
	ds_read_b128 v[168:171], v151 offset:50048
	s_waitcnt lgkmcnt(3)
	v_mfma_f32_16x16x32_bf16 v[70:73], v[140:143], v[176:179], v[70:73]
	v_mfma_f32_16x16x32_bf16 v[50:53], v[152:155], v[176:179], v[50:53]
	v_mfma_f32_16x16x32_bf16 v[30:33], v[156:159], v[176:179], v[30:33]
	v_mfma_f32_16x16x32_bf16 v[10:13], v[160:163], v[176:179], v[10:13]
	ds_read_b128 v[176:179], v138 offset:128
	global_load_dwordx4 v[74:77], v221, s[36:37] offset:2048
	global_load_dwordx4 v[140:143], v221, s[36:37] offset:3072
	global_load_dwordx4 v[96:99], v221, s[38:39] offset:2048
	global_load_dwordx4 v[152:155], v221, s[38:39] offset:3072
	global_load_dwordx4 v[92:95], v221, s[40:41] offset:2048
	global_load_dwordx4 v[156:159], v221, s[40:41] offset:3072
	global_load_dwordx4 v[88:91], v221, s[44:45] offset:2048
	global_load_dwordx4 v[160:163], v221, s[44:45] offset:3072
	s_waitcnt vmcnt(33)
	s_waitcnt lgkmcnt(3)
	v_mfma_f32_16x16x32_bf16 v[100:103], v[180:183], v[164:167], v[100:103]
	v_mfma_f32_16x16x32_bf16 v[62:65], v[184:187], v[164:167], v[62:65]
	v_mfma_f32_16x16x32_bf16 v[42:45], v[188:191], v[164:167], v[42:45]
	v_mfma_f32_16x16x32_bf16 v[22:25], v[192:195], v[164:167], v[22:25]
	ds_read_b128 v[164:167], v151 offset:16832
	s_waitcnt lgkmcnt(3)
	v_mfma_f32_16x16x32_bf16 v[80:83], v[180:183], v[172:175], v[80:83]
	v_mfma_f32_16x16x32_bf16 v[58:61], v[184:187], v[172:175], v[58:61]
	v_mfma_f32_16x16x32_bf16 v[38:41], v[188:191], v[172:175], v[38:41]
	v_mfma_f32_16x16x32_bf16 v[18:21], v[192:195], v[172:175], v[18:21]
	ds_read_b128 v[172:175], v151 offset:33472
	s_waitcnt lgkmcnt(3)
	v_mfma_f32_16x16x32_bf16 v[84:87], v[180:183], v[168:171], v[84:87]
	v_mfma_f32_16x16x32_bf16 v[54:57], v[184:187], v[168:171], v[54:57]
	v_mfma_f32_16x16x32_bf16 v[34:37], v[188:191], v[168:171], v[34:37]
	v_mfma_f32_16x16x32_bf16 v[14:17], v[192:195], v[168:171], v[14:17]
	ds_read_b128 v[168:171], v151 offset:50112
	s_waitcnt lgkmcnt(3)
	v_mfma_f32_16x16x32_bf16 v[70:73], v[180:183], v[176:179], v[70:73]
	v_mfma_f32_16x16x32_bf16 v[50:53], v[184:187], v[176:179], v[50:53]
	v_mfma_f32_16x16x32_bf16 v[30:33], v[188:191], v[176:179], v[30:33]
	v_mfma_f32_16x16x32_bf16 v[10:13], v[192:195], v[176:179], v[10:13]
	ds_read_b128 v[176:179], v138 offset:192
	s_waitcnt vmcnt(32)
	s_waitcnt lgkmcnt(3)
	v_mfma_f32_16x16x32_bf16 v[100:103], v[196:199], v[164:167], v[100:103]
	v_mfma_f32_16x16x32_bf16 v[62:65], v[200:203], v[164:167], v[62:65]
	v_mfma_f32_16x16x32_bf16 v[42:45], v[204:207], v[164:167], v[42:45]
	v_mfma_f32_16x16x32_bf16 v[22:25], v[208:211], v[164:167], v[22:25]
	ds_read_b128 v[164:167], v151 offset:16896
	s_waitcnt lgkmcnt(3)
	v_mfma_f32_16x16x32_bf16 v[80:83], v[196:199], v[172:175], v[80:83]
	v_mfma_f32_16x16x32_bf16 v[58:61], v[200:203], v[172:175], v[58:61]
	v_mfma_f32_16x16x32_bf16 v[38:41], v[204:207], v[172:175], v[38:41]
	v_mfma_f32_16x16x32_bf16 v[18:21], v[208:211], v[172:175], v[18:21]
	ds_read_b128 v[172:175], v151 offset:33536
	s_waitcnt lgkmcnt(3)
	v_mfma_f32_16x16x32_bf16 v[84:87], v[196:199], v[168:171], v[84:87]
	v_mfma_f32_16x16x32_bf16 v[54:57], v[200:203], v[168:171], v[54:57]
	v_mfma_f32_16x16x32_bf16 v[34:37], v[204:207], v[168:171], v[34:37]
	v_mfma_f32_16x16x32_bf16 v[14:17], v[208:211], v[168:171], v[14:17]
	ds_read_b128 v[168:171], v151 offset:50176
	s_waitcnt lgkmcnt(3)
	v_mfma_f32_16x16x32_bf16 v[70:73], v[196:199], v[176:179], v[70:73]
	v_mfma_f32_16x16x32_bf16 v[50:53], v[200:203], v[176:179], v[50:53]
	v_mfma_f32_16x16x32_bf16 v[30:33], v[204:207], v[176:179], v[30:33]
	v_mfma_f32_16x16x32_bf16 v[10:13], v[208:211], v[176:179], v[10:13]
	ds_read_b128 v[176:179], v138 offset:256
	global_load_dwordx4 v[180:183], v237, s[36:37] offset:0
	global_load_dwordx4 v[196:199], v237, s[36:37] offset:1024
	global_load_dwordx4 v[184:187], v237, s[38:39] offset:0
	global_load_dwordx4 v[200:203], v237, s[38:39] offset:1024
	global_load_dwordx4 v[188:191], v237, s[40:41] offset:0
	global_load_dwordx4 v[204:207], v237, s[40:41] offset:1024
	global_load_dwordx4 v[192:195], v237, s[44:45] offset:0
	global_load_dwordx4 v[208:211], v237, s[44:45] offset:1024
	s_waitcnt vmcnt(33)
	s_waitcnt lgkmcnt(3)
	v_mfma_f32_16x16x32_bf16 v[100:103], v[212:215], v[164:167], v[100:103]
	v_mfma_f32_16x16x32_bf16 v[62:65], v[216:219], v[164:167], v[62:65]
	v_mfma_f32_16x16x32_bf16 v[42:45], v[240:243], v[164:167], v[42:45]
	v_mfma_f32_16x16x32_bf16 v[22:25], v[244:247], v[164:167], v[22:25]
	ds_read_b128 v[164:167], v151 offset:16960
	s_waitcnt lgkmcnt(3)
	v_mfma_f32_16x16x32_bf16 v[80:83], v[212:215], v[172:175], v[80:83]
	v_mfma_f32_16x16x32_bf16 v[58:61], v[216:219], v[172:175], v[58:61]
	v_mfma_f32_16x16x32_bf16 v[38:41], v[240:243], v[172:175], v[38:41]
	v_mfma_f32_16x16x32_bf16 v[18:21], v[244:247], v[172:175], v[18:21]
	ds_read_b128 v[172:175], v151 offset:33600
	s_waitcnt lgkmcnt(3)
	v_mfma_f32_16x16x32_bf16 v[84:87], v[212:215], v[168:171], v[84:87]
	v_mfma_f32_16x16x32_bf16 v[54:57], v[216:219], v[168:171], v[54:57]
	v_mfma_f32_16x16x32_bf16 v[34:37], v[240:243], v[168:171], v[34:37]
	v_mfma_f32_16x16x32_bf16 v[14:17], v[244:247], v[168:171], v[14:17]
	ds_read_b128 v[168:171], v151 offset:50240
	s_waitcnt lgkmcnt(3)
	v_mfma_f32_16x16x32_bf16 v[70:73], v[212:215], v[176:179], v[70:73]
	v_mfma_f32_16x16x32_bf16 v[50:53], v[216:219], v[176:179], v[50:53]
	v_mfma_f32_16x16x32_bf16 v[30:33], v[240:243], v[176:179], v[30:33]
	v_mfma_f32_16x16x32_bf16 v[10:13], v[244:247], v[176:179], v[10:13]
	ds_read_b128 v[176:179], v138 offset:320
	s_waitcnt vmcnt(32)
	s_waitcnt lgkmcnt(3)
	v_mfma_f32_16x16x32_bf16 v[100:103], v[66:69], v[164:167], v[100:103]
	v_mfma_f32_16x16x32_bf16 v[62:65], v[46:49], v[164:167], v[62:65]
	v_mfma_f32_16x16x32_bf16 v[42:45], v[26:29], v[164:167], v[42:45]
	v_mfma_f32_16x16x32_bf16 v[22:25], v[6:9], v[164:167], v[22:25]
	ds_read_b128 v[164:167], v151 offset:17024
	s_waitcnt lgkmcnt(3)
	v_mfma_f32_16x16x32_bf16 v[80:83], v[66:69], v[172:175], v[80:83]
	v_mfma_f32_16x16x32_bf16 v[58:61], v[46:49], v[172:175], v[58:61]
	v_mfma_f32_16x16x32_bf16 v[38:41], v[26:29], v[172:175], v[38:41]
	v_mfma_f32_16x16x32_bf16 v[18:21], v[6:9], v[172:175], v[18:21]
	ds_read_b128 v[172:175], v151 offset:33664
	s_waitcnt lgkmcnt(3)
	v_mfma_f32_16x16x32_bf16 v[84:87], v[66:69], v[168:171], v[84:87]
	v_mfma_f32_16x16x32_bf16 v[54:57], v[46:49], v[168:171], v[54:57]
	v_mfma_f32_16x16x32_bf16 v[34:37], v[26:29], v[168:171], v[34:37]
	v_mfma_f32_16x16x32_bf16 v[14:17], v[6:9], v[168:171], v[14:17]
	ds_read_b128 v[168:171], v151 offset:50304
	s_waitcnt lgkmcnt(3)
	v_mfma_f32_16x16x32_bf16 v[70:73], v[66:69], v[176:179], v[70:73]
	v_mfma_f32_16x16x32_bf16 v[50:53], v[46:49], v[176:179], v[50:53]
	v_mfma_f32_16x16x32_bf16 v[30:33], v[26:29], v[176:179], v[30:33]
	v_mfma_f32_16x16x32_bf16 v[10:13], v[6:9], v[176:179], v[10:13]
	ds_read_b128 v[176:179], v138 offset:384
	global_load_dwordx4 v[212:215], v237, s[36:37] offset:2048
	global_load_dwordx4 v[66:69], v237, s[36:37] offset:3072
	global_load_dwordx4 v[216:219], v237, s[38:39] offset:2048
	global_load_dwordx4 v[46:49], v237, s[38:39] offset:3072
	global_load_dwordx4 v[240:243], v237, s[40:41] offset:2048
	global_load_dwordx4 v[26:29], v237, s[40:41] offset:3072
	global_load_dwordx4 v[244:247], v237, s[44:45] offset:2048
	global_load_dwordx4 v[6:9], v237, s[44:45] offset:3072
	s_waitcnt vmcnt(17)
	s_waitcnt lgkmcnt(3)
	v_mfma_f32_16x16x32_bf16 v[100:103], v[74:77], v[164:167], v[100:103]
	v_mfma_f32_16x16x32_bf16 v[62:65], v[96:99], v[164:167], v[62:65]
	v_mfma_f32_16x16x32_bf16 v[42:45], v[92:95], v[164:167], v[42:45]
	v_mfma_f32_16x16x32_bf16 v[22:25], v[88:91], v[164:167], v[22:25]
	ds_read_b128 v[164:167], v151 offset:17088
	s_waitcnt lgkmcnt(3)
	v_mfma_f32_16x16x32_bf16 v[80:83], v[74:77], v[172:175], v[80:83]
	v_mfma_f32_16x16x32_bf16 v[58:61], v[96:99], v[172:175], v[58:61]
	v_mfma_f32_16x16x32_bf16 v[38:41], v[92:95], v[172:175], v[38:41]
	v_mfma_f32_16x16x32_bf16 v[18:21], v[88:91], v[172:175], v[18:21]
	ds_read_b128 v[172:175], v151 offset:33728
	s_waitcnt lgkmcnt(3)
	v_mfma_f32_16x16x32_bf16 v[84:87], v[74:77], v[168:171], v[84:87]
	v_mfma_f32_16x16x32_bf16 v[54:57], v[96:99], v[168:171], v[54:57]
	v_mfma_f32_16x16x32_bf16 v[34:37], v[92:95], v[168:171], v[34:37]
	v_mfma_f32_16x16x32_bf16 v[14:17], v[88:91], v[168:171], v[14:17]
	ds_read_b128 v[168:171], v151 offset:50368
	s_waitcnt lgkmcnt(3)
	v_mfma_f32_16x16x32_bf16 v[70:73], v[74:77], v[176:179], v[70:73]
	v_mfma_f32_16x16x32_bf16 v[50:53], v[96:99], v[176:179], v[50:53]
	v_mfma_f32_16x16x32_bf16 v[30:33], v[92:95], v[176:179], v[30:33]
	v_mfma_f32_16x16x32_bf16 v[10:13], v[88:91], v[176:179], v[10:13]
	ds_read_b128 v[176:179], v138 offset:448
	s_waitcnt vmcnt(16)
	s_waitcnt lgkmcnt(3)
	v_mfma_f32_16x16x32_bf16 v[100:103], v[140:143], v[164:167], v[100:103]
	v_mfma_f32_16x16x32_bf16 v[62:65], v[152:155], v[164:167], v[62:65]
	v_mfma_f32_16x16x32_bf16 v[42:45], v[156:159], v[164:167], v[42:45]
	v_mfma_f32_16x16x32_bf16 v[22:25], v[160:163], v[164:167], v[22:25]
	ds_read_b128 v[164:167], v151 offset:17152
	s_waitcnt lgkmcnt(3)
	v_mfma_f32_16x16x32_bf16 v[80:83], v[140:143], v[172:175], v[80:83]
	v_mfma_f32_16x16x32_bf16 v[58:61], v[152:155], v[172:175], v[58:61]
	v_mfma_f32_16x16x32_bf16 v[38:41], v[156:159], v[172:175], v[38:41]
	v_mfma_f32_16x16x32_bf16 v[18:21], v[160:163], v[172:175], v[18:21]
	ds_read_b128 v[172:175], v151 offset:33792
	s_waitcnt lgkmcnt(3)
	v_mfma_f32_16x16x32_bf16 v[84:87], v[140:143], v[168:171], v[84:87]
	v_mfma_f32_16x16x32_bf16 v[54:57], v[152:155], v[168:171], v[54:57]
	v_mfma_f32_16x16x32_bf16 v[34:37], v[156:159], v[168:171], v[34:37]
	v_mfma_f32_16x16x32_bf16 v[14:17], v[160:163], v[168:171], v[14:17]
	ds_read_b128 v[168:171], v151 offset:50432
	s_waitcnt lgkmcnt(3)
	v_mfma_f32_16x16x32_bf16 v[70:73], v[140:143], v[176:179], v[70:73]
	v_mfma_f32_16x16x32_bf16 v[50:53], v[152:155], v[176:179], v[50:53]
	v_mfma_f32_16x16x32_bf16 v[30:33], v[156:159], v[176:179], v[30:33]
	v_mfma_f32_16x16x32_bf16 v[10:13], v[160:163], v[176:179], v[10:13]
	ds_read_b128 v[176:179], v138 offset:512
	global_load_dwordx4 v[74:77], v238, s[36:37] offset:0
	global_load_dwordx4 v[140:143], v238, s[36:37] offset:1024
	global_load_dwordx4 v[96:99], v238, s[38:39] offset:0
	global_load_dwordx4 v[152:155], v238, s[38:39] offset:1024
	global_load_dwordx4 v[92:95], v238, s[40:41] offset:0
	global_load_dwordx4 v[156:159], v238, s[40:41] offset:1024
	global_load_dwordx4 v[88:91], v238, s[44:45] offset:0
	global_load_dwordx4 v[160:163], v238, s[44:45] offset:1024
	s_waitcnt vmcnt(17)
	s_waitcnt lgkmcnt(3)
	v_mfma_f32_16x16x32_bf16 v[100:103], v[180:183], v[164:167], v[100:103]
	v_mfma_f32_16x16x32_bf16 v[62:65], v[184:187], v[164:167], v[62:65]
	v_mfma_f32_16x16x32_bf16 v[42:45], v[188:191], v[164:167], v[42:45]
	v_mfma_f32_16x16x32_bf16 v[22:25], v[192:195], v[164:167], v[22:25]
	ds_read_b128 v[164:167], v151 offset:17216
	s_waitcnt lgkmcnt(3)
	v_mfma_f32_16x16x32_bf16 v[80:83], v[180:183], v[172:175], v[80:83]
	v_mfma_f32_16x16x32_bf16 v[58:61], v[184:187], v[172:175], v[58:61]
	v_mfma_f32_16x16x32_bf16 v[38:41], v[188:191], v[172:175], v[38:41]
	v_mfma_f32_16x16x32_bf16 v[18:21], v[192:195], v[172:175], v[18:21]
	ds_read_b128 v[172:175], v151 offset:33856
	s_waitcnt lgkmcnt(3)
	v_mfma_f32_16x16x32_bf16 v[84:87], v[180:183], v[168:171], v[84:87]
	v_mfma_f32_16x16x32_bf16 v[54:57], v[184:187], v[168:171], v[54:57]
	v_mfma_f32_16x16x32_bf16 v[34:37], v[188:191], v[168:171], v[34:37]
	v_mfma_f32_16x16x32_bf16 v[14:17], v[192:195], v[168:171], v[14:17]
	ds_read_b128 v[168:171], v151 offset:50496
	s_waitcnt lgkmcnt(3)
	v_mfma_f32_16x16x32_bf16 v[70:73], v[180:183], v[176:179], v[70:73]
	v_mfma_f32_16x16x32_bf16 v[50:53], v[184:187], v[176:179], v[50:53]
	v_mfma_f32_16x16x32_bf16 v[30:33], v[188:191], v[176:179], v[30:33]
	v_mfma_f32_16x16x32_bf16 v[10:13], v[192:195], v[176:179], v[10:13]
	ds_read_b128 v[176:179], v138 offset:576
	s_waitcnt vmcnt(16)
	s_waitcnt lgkmcnt(3)
	v_mfma_f32_16x16x32_bf16 v[100:103], v[196:199], v[164:167], v[100:103]
	v_mfma_f32_16x16x32_bf16 v[62:65], v[200:203], v[164:167], v[62:65]
	v_mfma_f32_16x16x32_bf16 v[42:45], v[204:207], v[164:167], v[42:45]
	v_mfma_f32_16x16x32_bf16 v[22:25], v[208:211], v[164:167], v[22:25]
	ds_read_b128 v[164:167], v151 offset:17280
	s_waitcnt lgkmcnt(3)
	v_mfma_f32_16x16x32_bf16 v[80:83], v[196:199], v[172:175], v[80:83]
	v_mfma_f32_16x16x32_bf16 v[58:61], v[200:203], v[172:175], v[58:61]
	v_mfma_f32_16x16x32_bf16 v[38:41], v[204:207], v[172:175], v[38:41]
	v_mfma_f32_16x16x32_bf16 v[18:21], v[208:211], v[172:175], v[18:21]
	ds_read_b128 v[172:175], v151 offset:33920
	s_waitcnt lgkmcnt(3)
	v_mfma_f32_16x16x32_bf16 v[84:87], v[196:199], v[168:171], v[84:87]
	v_mfma_f32_16x16x32_bf16 v[54:57], v[200:203], v[168:171], v[54:57]
	v_mfma_f32_16x16x32_bf16 v[34:37], v[204:207], v[168:171], v[34:37]
	v_mfma_f32_16x16x32_bf16 v[14:17], v[208:211], v[168:171], v[14:17]
	ds_read_b128 v[168:171], v151 offset:50560
	s_waitcnt lgkmcnt(3)
	v_mfma_f32_16x16x32_bf16 v[70:73], v[196:199], v[176:179], v[70:73]
	v_mfma_f32_16x16x32_bf16 v[50:53], v[200:203], v[176:179], v[50:53]
	v_mfma_f32_16x16x32_bf16 v[30:33], v[204:207], v[176:179], v[30:33]
	v_mfma_f32_16x16x32_bf16 v[10:13], v[208:211], v[176:179], v[10:13]
	ds_read_b128 v[176:179], v138 offset:640
	global_load_dwordx4 v[180:183], v238, s[36:37] offset:2048
	global_load_dwordx4 v[196:199], v238, s[36:37] offset:3072
	global_load_dwordx4 v[184:187], v238, s[38:39] offset:2048
	global_load_dwordx4 v[200:203], v238, s[38:39] offset:3072
	global_load_dwordx4 v[188:191], v238, s[40:41] offset:2048
	global_load_dwordx4 v[204:207], v238, s[40:41] offset:3072
	global_load_dwordx4 v[192:195], v238, s[44:45] offset:2048
	global_load_dwordx4 v[208:211], v238, s[44:45] offset:3072
	s_waitcnt vmcnt(17)
	s_waitcnt lgkmcnt(3)
	v_mfma_f32_16x16x32_bf16 v[100:103], v[212:215], v[164:167], v[100:103]
	v_mfma_f32_16x16x32_bf16 v[62:65], v[216:219], v[164:167], v[62:65]
	v_mfma_f32_16x16x32_bf16 v[42:45], v[240:243], v[164:167], v[42:45]
	v_mfma_f32_16x16x32_bf16 v[22:25], v[244:247], v[164:167], v[22:25]
	ds_read_b128 v[164:167], v151 offset:17344
	s_waitcnt lgkmcnt(3)
	v_mfma_f32_16x16x32_bf16 v[80:83], v[212:215], v[172:175], v[80:83]
	v_mfma_f32_16x16x32_bf16 v[58:61], v[216:219], v[172:175], v[58:61]
	v_mfma_f32_16x16x32_bf16 v[38:41], v[240:243], v[172:175], v[38:41]
	v_mfma_f32_16x16x32_bf16 v[18:21], v[244:247], v[172:175], v[18:21]
	ds_read_b128 v[172:175], v151 offset:33984
	s_waitcnt lgkmcnt(3)
	v_mfma_f32_16x16x32_bf16 v[84:87], v[212:215], v[168:171], v[84:87]
	v_mfma_f32_16x16x32_bf16 v[54:57], v[216:219], v[168:171], v[54:57]
	v_mfma_f32_16x16x32_bf16 v[34:37], v[240:243], v[168:171], v[34:37]
	v_mfma_f32_16x16x32_bf16 v[14:17], v[244:247], v[168:171], v[14:17]
	ds_read_b128 v[168:171], v151 offset:50624
	s_waitcnt lgkmcnt(3)
	v_mfma_f32_16x16x32_bf16 v[70:73], v[212:215], v[176:179], v[70:73]
	v_mfma_f32_16x16x32_bf16 v[50:53], v[216:219], v[176:179], v[50:53]
	v_mfma_f32_16x16x32_bf16 v[30:33], v[240:243], v[176:179], v[30:33]
	v_mfma_f32_16x16x32_bf16 v[10:13], v[244:247], v[176:179], v[10:13]
	ds_read_b128 v[176:179], v138 offset:704
	s_waitcnt vmcnt(16)
	s_waitcnt lgkmcnt(3)
	v_mfma_f32_16x16x32_bf16 v[100:103], v[66:69], v[164:167], v[100:103]
	v_mfma_f32_16x16x32_bf16 v[62:65], v[46:49], v[164:167], v[62:65]
	v_mfma_f32_16x16x32_bf16 v[42:45], v[26:29], v[164:167], v[42:45]
	v_mfma_f32_16x16x32_bf16 v[22:25], v[6:9], v[164:167], v[22:25]
	ds_read_b128 v[164:167], v151 offset:17408
	s_waitcnt lgkmcnt(3)
	v_mfma_f32_16x16x32_bf16 v[80:83], v[66:69], v[172:175], v[80:83]
	v_mfma_f32_16x16x32_bf16 v[58:61], v[46:49], v[172:175], v[58:61]
	v_mfma_f32_16x16x32_bf16 v[38:41], v[26:29], v[172:175], v[38:41]
	v_mfma_f32_16x16x32_bf16 v[18:21], v[6:9], v[172:175], v[18:21]
	ds_read_b128 v[172:175], v151 offset:34048
	s_waitcnt lgkmcnt(3)
	v_mfma_f32_16x16x32_bf16 v[84:87], v[66:69], v[168:171], v[84:87]
	v_mfma_f32_16x16x32_bf16 v[54:57], v[46:49], v[168:171], v[54:57]
	v_mfma_f32_16x16x32_bf16 v[34:37], v[26:29], v[168:171], v[34:37]
	v_mfma_f32_16x16x32_bf16 v[14:17], v[6:9], v[168:171], v[14:17]
	ds_read_b128 v[168:171], v151 offset:50688
	s_waitcnt lgkmcnt(3)
	v_mfma_f32_16x16x32_bf16 v[70:73], v[66:69], v[176:179], v[70:73]
	v_mfma_f32_16x16x32_bf16 v[50:53], v[46:49], v[176:179], v[50:53]
	v_mfma_f32_16x16x32_bf16 v[30:33], v[26:29], v[176:179], v[30:33]
	v_mfma_f32_16x16x32_bf16 v[10:13], v[6:9], v[176:179], v[10:13]
	ds_read_b128 v[176:179], v138 offset:768
	global_load_dwordx4 v[66:69], v220, s[46:47]
	global_load_dwordx4 v[46:49], v220, s[46:47] offset:64
	global_load_dwordx4 v[26:29], v220, s[46:47] offset:128
	global_load_dwordx4 v[6:9], v220, s[46:47] offset:192
	s_waitcnt vmcnt(13)
	s_waitcnt lgkmcnt(3)
	v_mfma_f32_16x16x32_bf16 v[100:103], v[74:77], v[164:167], v[100:103]
	v_mfma_f32_16x16x32_bf16 v[62:65], v[96:99], v[164:167], v[62:65]
	v_mfma_f32_16x16x32_bf16 v[42:45], v[92:95], v[164:167], v[42:45]
	v_mfma_f32_16x16x32_bf16 v[22:25], v[88:91], v[164:167], v[22:25]
	ds_read_b128 v[164:167], v151 offset:17472
	s_waitcnt lgkmcnt(3)
	v_mfma_f32_16x16x32_bf16 v[80:83], v[74:77], v[172:175], v[80:83]
	v_mfma_f32_16x16x32_bf16 v[58:61], v[96:99], v[172:175], v[58:61]
	v_mfma_f32_16x16x32_bf16 v[38:41], v[92:95], v[172:175], v[38:41]
	v_mfma_f32_16x16x32_bf16 v[18:21], v[88:91], v[172:175], v[18:21]
	ds_read_b128 v[172:175], v151 offset:34112
	s_waitcnt lgkmcnt(3)
	v_mfma_f32_16x16x32_bf16 v[84:87], v[74:77], v[168:171], v[84:87]
	v_mfma_f32_16x16x32_bf16 v[54:57], v[96:99], v[168:171], v[54:57]
	v_mfma_f32_16x16x32_bf16 v[34:37], v[92:95], v[168:171], v[34:37]
	v_mfma_f32_16x16x32_bf16 v[14:17], v[88:91], v[168:171], v[14:17]
	ds_read_b128 v[168:171], v151 offset:50752
	s_waitcnt lgkmcnt(3)
	v_mfma_f32_16x16x32_bf16 v[70:73], v[74:77], v[176:179], v[70:73]
	v_mfma_f32_16x16x32_bf16 v[50:53], v[96:99], v[176:179], v[50:53]
	v_mfma_f32_16x16x32_bf16 v[30:33], v[92:95], v[176:179], v[30:33]
	v_mfma_f32_16x16x32_bf16 v[10:13], v[88:91], v[176:179], v[10:13]
	ds_read_b128 v[176:179], v138 offset:832
	s_waitcnt vmcnt(12)
	s_waitcnt lgkmcnt(3)
	v_mfma_f32_16x16x32_bf16 v[100:103], v[140:143], v[164:167], v[100:103]
	v_mfma_f32_16x16x32_bf16 v[62:65], v[152:155], v[164:167], v[62:65]
	v_mfma_f32_16x16x32_bf16 v[42:45], v[156:159], v[164:167], v[42:45]
	v_mfma_f32_16x16x32_bf16 v[22:25], v[160:163], v[164:167], v[22:25]
	ds_read_b128 v[164:167], v151 offset:17536
	s_waitcnt lgkmcnt(3)
	v_mfma_f32_16x16x32_bf16 v[80:83], v[140:143], v[172:175], v[80:83]
	v_mfma_f32_16x16x32_bf16 v[58:61], v[152:155], v[172:175], v[58:61]
	v_mfma_f32_16x16x32_bf16 v[38:41], v[156:159], v[172:175], v[38:41]
	v_mfma_f32_16x16x32_bf16 v[18:21], v[160:163], v[172:175], v[18:21]
	ds_read_b128 v[172:175], v151 offset:34176
	s_waitcnt lgkmcnt(3)
	v_mfma_f32_16x16x32_bf16 v[84:87], v[140:143], v[168:171], v[84:87]
	v_mfma_f32_16x16x32_bf16 v[54:57], v[152:155], v[168:171], v[54:57]
	v_mfma_f32_16x16x32_bf16 v[34:37], v[156:159], v[168:171], v[34:37]
	v_mfma_f32_16x16x32_bf16 v[14:17], v[160:163], v[168:171], v[14:17]
	ds_read_b128 v[168:171], v151 offset:50816
	s_waitcnt lgkmcnt(3)
	v_mfma_f32_16x16x32_bf16 v[70:73], v[140:143], v[176:179], v[70:73]
	v_mfma_f32_16x16x32_bf16 v[50:53], v[152:155], v[176:179], v[50:53]
	v_mfma_f32_16x16x32_bf16 v[30:33], v[156:159], v[176:179], v[30:33]
	v_mfma_f32_16x16x32_bf16 v[10:13], v[160:163], v[176:179], v[10:13]
	ds_read_b128 v[176:179], v138 offset:896
	s_waitcnt vmcnt(5)
	s_waitcnt lgkmcnt(3)
	v_mfma_f32_16x16x32_bf16 v[100:103], v[180:183], v[164:167], v[100:103]
	v_mfma_f32_16x16x32_bf16 v[62:65], v[184:187], v[164:167], v[62:65]
	v_mfma_f32_16x16x32_bf16 v[42:45], v[188:191], v[164:167], v[42:45]
	v_mfma_f32_16x16x32_bf16 v[22:25], v[192:195], v[164:167], v[22:25]
	ds_read_b128 v[164:167], v151 offset:17600
	s_waitcnt lgkmcnt(3)
	v_mfma_f32_16x16x32_bf16 v[80:83], v[180:183], v[172:175], v[80:83]
	v_mfma_f32_16x16x32_bf16 v[58:61], v[184:187], v[172:175], v[58:61]
	v_mfma_f32_16x16x32_bf16 v[38:41], v[188:191], v[172:175], v[38:41]
	v_mfma_f32_16x16x32_bf16 v[18:21], v[192:195], v[172:175], v[18:21]
	ds_read_b128 v[172:175], v151 offset:34240
	s_waitcnt lgkmcnt(3)
	v_mfma_f32_16x16x32_bf16 v[84:87], v[180:183], v[168:171], v[84:87]
	v_mfma_f32_16x16x32_bf16 v[54:57], v[184:187], v[168:171], v[54:57]
	v_mfma_f32_16x16x32_bf16 v[34:37], v[188:191], v[168:171], v[34:37]
	v_mfma_f32_16x16x32_bf16 v[14:17], v[192:195], v[168:171], v[14:17]
	ds_read_b128 v[168:171], v151 offset:50880
	s_waitcnt lgkmcnt(3)
	v_mfma_f32_16x16x32_bf16 v[70:73], v[180:183], v[176:179], v[70:73]
	v_mfma_f32_16x16x32_bf16 v[50:53], v[184:187], v[176:179], v[50:53]
	v_mfma_f32_16x16x32_bf16 v[30:33], v[188:191], v[176:179], v[30:33]
	v_mfma_f32_16x16x32_bf16 v[10:13], v[192:195], v[176:179], v[10:13]
	ds_read_b128 v[176:179], v138 offset:960
	s_waitcnt vmcnt(4)
	s_waitcnt lgkmcnt(3)
	v_mfma_f32_16x16x32_bf16 v[100:103], v[196:199], v[164:167], v[100:103]
	v_mfma_f32_16x16x32_bf16 v[62:65], v[200:203], v[164:167], v[62:65]
	v_mfma_f32_16x16x32_bf16 v[42:45], v[204:207], v[164:167], v[42:45]
	v_mfma_f32_16x16x32_bf16 v[22:25], v[208:211], v[164:167], v[22:25]
	s_waitcnt lgkmcnt(2)
	v_mfma_f32_16x16x32_bf16 v[80:83], v[196:199], v[172:175], v[80:83]
	v_mfma_f32_16x16x32_bf16 v[58:61], v[200:203], v[172:175], v[58:61]
	v_mfma_f32_16x16x32_bf16 v[38:41], v[204:207], v[172:175], v[38:41]
	v_mfma_f32_16x16x32_bf16 v[18:21], v[208:211], v[172:175], v[18:21]
	s_waitcnt lgkmcnt(1)
	v_mfma_f32_16x16x32_bf16 v[84:87], v[196:199], v[168:171], v[84:87]
	v_mfma_f32_16x16x32_bf16 v[54:57], v[200:203], v[168:171], v[54:57]
	v_mfma_f32_16x16x32_bf16 v[34:37], v[204:207], v[168:171], v[34:37]
	v_mfma_f32_16x16x32_bf16 v[14:17], v[208:211], v[168:171], v[14:17]
	s_waitcnt lgkmcnt(0)
	v_mfma_f32_16x16x32_bf16 v[70:73], v[196:199], v[176:179], v[70:73]
	v_mfma_f32_16x16x32_bf16 v[50:53], v[200:203], v[176:179], v[50:53]
	v_mfma_f32_16x16x32_bf16 v[30:33], v[204:207], v[176:179], v[30:33]
	v_mfma_f32_16x16x32_bf16 v[10:13], v[208:211], v[176:179], v[10:13]
	s_waitcnt vmcnt(3)
	v_add_f32_e32 v76, v66, v100
	v_mul_f32_e32 v76, 0xbfb8aa3b, v76
	v_exp_f32_e32 v76, v76
	s_waitcnt vmcnt(1)
	v_lshlrev_b32_e32 v94, 16, v78
	s_waitcnt vmcnt(0)
	v_or_b32_e32 v88, s0, v146
	v_lshlrev_b32_e32 v74, 1, v88
	v_add_f32_e32 v76, 1.0, v76
	v_rcp_f32_e32 v90, v76
	v_add_f32_e32 v76, v67, v101
	v_mul_f32_e32 v76, 0xbfb8aa3b, v76
	v_exp_f32_e32 v76, v76
	v_add_u32_e32 v75, v150, v74
	v_lshlrev_b32_e32 v95, 16, v79
	v_add_u32_e32 v97, 0x4000, v75
	v_add_f32_e32 v76, 1.0, v76
	v_rcp_f32_e32 v92, v76
	v_add_f32_e32 v76, v68, v102
	v_mul_f32_e32 v76, 0xbfb8aa3b, v76
	v_exp_f32_e32 v76, v76
	v_mul_f32_e32 v75, 0xbfb8aa3b, v95
	v_exp_f32_e32 v75, v75
	v_and_b32_e32 v100, 0xffff0000, v78
	v_add_f32_e32 v76, 1.0, v76
	v_rcp_f32_e32 v91, v76
	v_add_f32_e32 v76, v69, v103
	v_mul_f32_e32 v76, 0xbfb8aa3b, v76
	v_exp_f32_e32 v76, v76
	v_and_b32_e32 v101, 0xffff0000, v79
	v_add_f32_e32 v75, 1.0, v75
	v_rcp_f32_e32 v99, v75
	v_add_f32_e32 v76, 1.0, v76
	v_rcp_f32_e32 v93, v76
	v_mul_f32_e32 v76, 0xbfb8aa3b, v94
	v_exp_f32_e32 v76, v76
	v_mul_f32_e32 v75, 0xbfb8aa3b, v101
	v_exp_f32_e32 v75, v75
	v_ashrrev_i32_e32 v89, 31, v88
	v_add_f32_e32 v76, 1.0, v76
	v_rcp_f32_e32 v98, v76
	v_mul_f32_e32 v76, 0xbfb8aa3b, v100
	v_exp_f32_e32 v76, v76
	v_add_f32_e32 v75, 1.0, v75
	v_rcp_f32_e32 v103, v75
	v_pk_mul_f32 v[94:95], v[98:99], v[94:95]
	v_add_f32_e32 v76, 1.0, v76
	v_rcp_f32_e32 v102, v76
	ds_read2_b64 v[76:79], v97 offset0:32 offset1:36
	v_lshlrev_b32_e32 v98, 16, v132
	v_lshlrev_b32_e32 v99, 16, v133
	v_readlane_b32 s0, v251, 55
	v_readlane_b32 s1, v251, 56
	s_waitcnt lgkmcnt(0)
	v_lshlrev_b32_e32 v137, 16, v77
	v_lshlrev_b32_e32 v136, 16, v76
	v_pk_mul_f32 v[90:91], v[90:91], v[136:137]
	v_and_b32_e32 v77, 0xffff0000, v77
	v_and_b32_e32 v76, 0xffff0000, v76
	v_pk_mul_f32 v[90:91], v[94:95], v[90:91]
	v_pk_mul_f32 v[76:77], v[92:93], v[76:77]
	v_pk_mul_f32 v[92:93], v[102:103], v[100:101]
	s_nop 0
	v_pk_mul_f32 v[76:77], v[92:93], v[76:77]
	s_nop 0
	v_cvt_pk_bf16_f32 v77, v91, v77
	v_cvt_pk_bf16_f32 v76, v90, v76
	v_lshlrev_b64 v[90:91], 1, v[88:89]
	v_lshl_add_u64 v[88:89], v[134:135], 0, v[90:91]
	global_store_dwordx2 v[88:89], v[76:77], off offset:2560
	v_add_f32_e32 v76, v66, v80
	v_add_f32_e32 v80, v69, v83
	v_mul_f32_e32 v80, 0xbfb8aa3b, v80
	v_exp_f32_e32 v80, v80
	v_add_f32_e32 v77, v67, v81
	v_mul_f32_e32 v77, 0xbfb8aa3b, v77
	v_add3_u32 v75, 0, v236, v74
	v_add_f32_e32 v80, 1.0, v80
	v_rcp_f32_e32 v93, v80
	v_mul_f32_e32 v80, 0xbfb8aa3b, v98
	v_exp_f32_e32 v80, v80
	v_exp_f32_e32 v77, v77
	v_add_u32_e32 v94, 0x4000, v75
	v_mul_f32_e32 v75, 0xbfb8aa3b, v99
	v_exp_f32_e32 v75, v75
	v_add_f32_e32 v80, 1.0, v80
	v_and_b32_e32 v102, 0xffff0000, v132
	v_add_f32_e32 v77, 1.0, v77
	v_rcp_f32_e32 v100, v80
	v_mul_f32_e32 v80, 0xbfb8aa3b, v102
	v_rcp_f32_e32 v92, v77
	v_add_f32_e32 v77, v68, v82
	v_exp_f32_e32 v80, v80
	v_mul_f32_e32 v76, 0xbfb8aa3b, v76
	v_mul_f32_e32 v77, 0xbfb8aa3b, v77
	v_and_b32_e32 v103, 0xffff0000, v133
	v_add_f32_e32 v75, 1.0, v75
	v_exp_f32_e32 v76, v76
	v_exp_f32_e32 v77, v77
	v_rcp_f32_e32 v101, v75
	v_mul_f32_e32 v75, 0xbfb8aa3b, v103
	v_exp_f32_e32 v75, v75
	v_add_f32_e32 v80, 1.0, v80
	v_rcp_f32_e32 v132, v80
	ds_read2_b64 v[80:83], v94 offset0:32 offset1:36
	v_add_f32_e32 v76, 1.0, v76
	v_add_f32_e32 v77, 1.0, v77
	v_rcp_f32_e32 v76, v76
	v_rcp_f32_e32 v77, v77
	v_add_f32_e32 v75, 1.0, v75
	v_rcp_f32_e32 v133, v75
	s_waitcnt lgkmcnt(0)
	v_lshlrev_b32_e32 v135, 16, v81
	v_lshlrev_b32_e32 v134, 16, v80
	v_pk_mul_f32 v[76:77], v[76:77], v[134:135]
	v_pk_mul_f32 v[98:99], v[100:101], v[98:99]
	v_and_b32_e32 v81, 0xffff0000, v81
	v_and_b32_e32 v80, 0xffff0000, v80
	v_pk_mul_f32 v[76:77], v[98:99], v[76:77]
	v_pk_mul_f32 v[80:81], v[92:93], v[80:81]
	v_pk_mul_f32 v[92:93], v[132:133], v[102:103]
	s_nop 0
	v_pk_mul_f32 v[80:81], v[92:93], v[80:81]
	s_nop 0
	v_cvt_pk_bf16_f32 v77, v77, v81
	v_cvt_pk_bf16_f32 v76, v76, v80
	v_or_b32_e32 v75, s88, v147
	v_mov_b64_e32 v[92:93], s[0:1]
	s_movk_i32 s4, 0x2800
	v_or_b32_e32 v96, 32, v1
	v_mad_i64_i32 v[80:81], s[0:1], v75, s4, v[92:93]
	v_mul_u32_u24_e32 v75, 0x410, v96
	v_lshlrev_b32_e32 v98, 16, v130
	v_add3_u32 v134, 0, v75, v74
	v_add_f32_e32 v74, v66, v84
	v_mul_f32_e32 v84, 0xbfb8aa3b, v98
	v_exp_f32_e32 v84, v84
	v_add_f32_e32 v75, v67, v85
	v_and_b32_e32 v102, 0xffff0000, v130
	v_lshl_add_u64 v[80:81], v[80:81], 0, v[90:91]
	v_add_f32_e32 v84, 1.0, v84
	v_mul_f32_e32 v75, 0xbfb8aa3b, v75
	v_rcp_f32_e32 v100, v84
	v_mul_f32_e32 v84, 0xbfb8aa3b, v102
	global_store_dwordx2 v[80:81], v[76:77], off offset:2560
	v_exp_f32_e32 v75, v75
	v_add_f32_e32 v77, v69, v87
	v_exp_f32_e32 v84, v84
	v_mul_f32_e32 v77, 0xbfb8aa3b, v77
	v_exp_f32_e32 v77, v77
	v_add_f32_e32 v75, 1.0, v75
	v_add_f32_e32 v84, 1.0, v84
	v_add_u32_e32 v95, 0x4000, v134
	v_rcp_f32_e32 v76, v75
	v_add_f32_e32 v75, v68, v86
	v_rcp_f32_e32 v130, v84
	ds_read2_b64 v[84:87], v95 offset0:32 offset1:36
	v_add_f32_e32 v77, 1.0, v77
	v_lshlrev_b32_e32 v99, 16, v131
	v_mul_f32_e32 v74, 0xbfb8aa3b, v74
	v_mul_f32_e32 v75, 0xbfb8aa3b, v75
	v_rcp_f32_e32 v77, v77
	v_mul_f32_e32 v101, 0xbfb8aa3b, v99
	v_exp_f32_e32 v74, v74
	v_exp_f32_e32 v75, v75
	v_exp_f32_e32 v101, v101
	v_and_b32_e32 v103, 0xffff0000, v131
	s_waitcnt lgkmcnt(0)
	v_lshlrev_b32_e32 v133, 16, v85
	v_lshlrev_b32_e32 v132, 16, v84
	v_and_b32_e32 v85, 0xffff0000, v85
	v_and_b32_e32 v84, 0xffff0000, v84
	v_add_f32_e32 v67, v67, v71
	v_pk_mul_f32 v[76:77], v[76:77], v[84:85]
	v_mul_f32_e32 v84, 0xbfb8aa3b, v103
	v_mul_f32_e32 v67, 0xbfb8aa3b, v67
	v_add_f32_e32 v74, 1.0, v74
	v_add_f32_e32 v75, 1.0, v75
	v_add_f32_e32 v101, 1.0, v101
	v_exp_f32_e32 v84, v84
	v_exp_f32_e32 v67, v67
	v_rcp_f32_e32 v74, v74
	v_rcp_f32_e32 v75, v75
	v_rcp_f32_e32 v101, v101
	v_add_f32_e32 v84, 1.0, v84
	v_add_f32_e32 v67, 1.0, v67
	v_pk_mul_f32 v[74:75], v[74:75], v[132:133]
	v_pk_mul_f32 v[98:99], v[100:101], v[98:99]
	v_rcp_f32_e32 v131, v84
	v_add_f32_e32 v66, v66, v70
	v_rcp_f32_e32 v70, v67
	v_add_f32_e32 v67, v68, v72
	v_add_f32_e32 v68, v69, v73
	v_pk_mul_f32 v[74:75], v[98:99], v[74:75]
	v_mul_f32_e32 v68, 0xbfb8aa3b, v68
	v_and_b32_e32 v98, 0xffff0000, v128
	v_exp_f32_e32 v68, v68
	v_mul_f32_e32 v73, 0xbfb8aa3b, v98
	v_exp_f32_e32 v73, v73
	v_pk_mul_f32 v[84:85], v[130:131], v[102:103]
	v_add_f32_e32 v68, 1.0, v68
	v_pk_mul_f32 v[76:77], v[84:85], v[76:77]
	s_nop 0
	v_cvt_pk_bf16_f32 v74, v74, v76
	v_cvt_pk_bf16_f32 v75, v75, v77
	v_rcp_f32_e32 v71, v68
	v_lshlrev_b32_e32 v69, 16, v129
	v_lshlrev_b32_e32 v68, 16, v128
	v_add_f32_e32 v73, 1.0, v73
	v_mul_f32_e32 v66, 0xbfb8aa3b, v66
	v_mul_f32_e32 v67, 0xbfb8aa3b, v67
	v_mul_f32_e32 v72, 0xbfb8aa3b, v68
	v_rcp_f32_e32 v100, v73
	v_mul_f32_e32 v73, 0xbfb8aa3b, v69
	v_or_b32_e32 v76, s88, v96
	v_exp_f32_e32 v66, v66
	v_exp_f32_e32 v67, v67
	v_exp_f32_e32 v72, v72
	v_exp_f32_e32 v73, v73
	v_mad_i64_i32 v[76:77], s[0:1], v76, s4, v[92:93]
	v_lshl_add_u64 v[84:85], v[76:77], 0, v[90:91]
	v_add_u32_e32 v96, 0x8000, v134
	global_store_dwordx2 v[84:85], v[74:75], off offset:2560
	ds_read2_b64 v[74:77], v96 offset0:64 offset1:68
	v_add_f32_e32 v66, 1.0, v66
	v_add_f32_e32 v67, 1.0, v67
	v_add_f32_e32 v72, 1.0, v72
	v_add_f32_e32 v73, 1.0, v73
	v_rcp_f32_e32 v66, v66
	v_rcp_f32_e32 v67, v67
	v_rcp_f32_e32 v72, v72
	v_rcp_f32_e32 v73, v73
	s_waitcnt lgkmcnt(0)
	v_lshlrev_b32_e32 v103, 16, v75
	v_lshlrev_b32_e32 v102, 16, v74
	v_pk_mul_f32 v[66:67], v[66:67], v[102:103]
	v_pk_mul_f32 v[68:69], v[72:73], v[68:69]
	v_and_b32_e32 v99, 0xffff0000, v129
	v_pk_mul_f32 v[66:67], v[68:69], v[66:67]
	v_and_b32_e32 v69, 0xffff0000, v75
	v_and_b32_e32 v68, 0xffff0000, v74
	v_pk_mul_f32 v[68:69], v[70:71], v[68:69]
	v_mul_f32_e32 v70, 0xbfb8aa3b, v99
	v_exp_f32_e32 v70, v70
	v_or3_b32 v1, v1, s88, 48
	v_and_b32_e32 v72, 0xffff0000, v126
	v_and_b32_e32 v73, 0xffff0000, v127
	v_add_f32_e32 v70, 1.0, v70
	v_rcp_f32_e32 v101, v70
	v_readlane_b32 s10, v255, 3
	v_readlane_b32 s11, v255, 4
	v_pk_mul_f32 v[70:71], v[100:101], v[98:99]
	s_nop 0
	v_pk_mul_f32 v[68:69], v[70:71], v[68:69]
	s_nop 0
	v_cvt_pk_bf16_f32 v69, v67, v69
	v_cvt_pk_bf16_f32 v68, v66, v68
	v_mad_i64_i32 v[66:67], s[0:1], v1, s4, v[92:93]
	v_add_f32_e32 v1, v46, v62
	v_mul_f32_e32 v1, 0xbfb8aa3b, v1
	v_exp_f32_e32 v1, v1
	v_lshl_add_u64 v[66:67], v[66:67], 0, v[90:91]
	global_store_dwordx2 v[66:67], v[68:69], off offset:2560
	v_lshlrev_b32_e32 v91, 16, v79
	v_add_f32_e32 v1, 1.0, v1
	v_rcp_f32_e32 v62, v1
	v_add_f32_e32 v1, v47, v63
	v_mul_f32_e32 v1, 0xbfb8aa3b, v1
	v_exp_f32_e32 v1, v1
	v_lshlrev_b32_e32 v90, 16, v78
	v_add_f32_e32 v1, 1.0, v1
	v_rcp_f32_e32 v68, v1
	v_add_f32_e32 v1, v48, v64
	v_mul_f32_e32 v1, 0xbfb8aa3b, v1
	v_exp_f32_e32 v1, v1
	v_lshlrev_b32_e32 v64, 16, v126
	v_add_f32_e32 v1, 1.0, v1
	v_rcp_f32_e32 v63, v1
	v_add_f32_e32 v1, v49, v65
	v_mul_f32_e32 v1, 0xbfb8aa3b, v1
	v_exp_f32_e32 v1, v1
	v_lshlrev_b32_e32 v65, 16, v127
	v_pk_mul_f32 v[62:63], v[62:63], v[90:91]
	v_add_f32_e32 v1, 1.0, v1
	v_rcp_f32_e32 v69, v1
	v_mul_f32_e32 v1, 0xbfb8aa3b, v64
	v_exp_f32_e32 v1, v1
	s_nop 0
	v_add_f32_e32 v1, 1.0, v1
	v_rcp_f32_e32 v70, v1
	v_mul_f32_e32 v1, 0xbfb8aa3b, v72
	v_exp_f32_e32 v1, v1
	s_nop 0
	v_add_f32_e32 v1, 1.0, v1
	v_rcp_f32_e32 v74, v1
	v_mul_f32_e32 v1, 0xbfb8aa3b, v65
	v_exp_f32_e32 v1, v1
	s_nop 0
	v_add_f32_e32 v1, 1.0, v1
	v_rcp_f32_e32 v71, v1
	v_mul_f32_e32 v1, 0xbfb8aa3b, v73
	v_exp_f32_e32 v1, v1
	v_pk_mul_f32 v[64:65], v[70:71], v[64:65]
	s_nop 0
	v_pk_mul_f32 v[62:63], v[64:65], v[62:63]
	v_add_f32_e32 v1, 1.0, v1
	v_rcp_f32_e32 v75, v1
	v_and_b32_e32 v65, 0xffff0000, v79
	v_and_b32_e32 v64, 0xffff0000, v78
	v_pk_mul_f32 v[64:65], v[68:69], v[64:65]
	v_pk_mul_f32 v[68:69], v[74:75], v[72:73]
	s_nop 0
	v_pk_mul_f32 v[64:65], v[68:69], v[64:65]
	s_nop 0
	v_cvt_pk_bf16_f32 v63, v63, v65
	v_add_f32_e32 v1, v46, v58
	v_mul_f32_e32 v1, 0xbfb8aa3b, v1
	v_exp_f32_e32 v1, v1
	v_cvt_pk_bf16_f32 v62, v62, v64
	v_add_f32_e32 v1, 1.0, v1
	v_rcp_f32_e32 v58, v1
	v_add_f32_e32 v1, v47, v59
	v_mul_f32_e32 v1, 0xbfb8aa3b, v1
	v_exp_f32_e32 v1, v1
	s_nop 0
	v_add_f32_e32 v1, 1.0, v1
	global_store_dwordx2 v[88:89], v[62:63], off offset:2592
	v_rcp_f32_e32 v62, v1
	v_add_f32_e32 v1, v48, v60
	v_mul_f32_e32 v1, 0xbfb8aa3b, v1
	v_exp_f32_e32 v1, v1
	v_lshlrev_b32_e32 v60, 16, v124
	v_and_b32_e32 v68, 0xffff0000, v124
	v_and_b32_e32 v69, 0xffff0000, v125
	v_add_f32_e32 v1, 1.0, v1
	v_rcp_f32_e32 v59, v1
	v_add_f32_e32 v1, v49, v61
	v_mul_f32_e32 v1, 0xbfb8aa3b, v1
	v_exp_f32_e32 v1, v1
	v_lshlrev_b32_e32 v61, 16, v125
	v_lshlrev_b32_e32 v73, 16, v83
	v_lshlrev_b32_e32 v72, 16, v82
	v_add_f32_e32 v1, 1.0, v1
	v_rcp_f32_e32 v63, v1
	v_mul_f32_e32 v1, 0xbfb8aa3b, v60
	v_exp_f32_e32 v1, v1
	v_pk_mul_f32 v[58:59], v[58:59], v[72:73]
	v_add_f32_e32 v1, 1.0, v1
	v_rcp_f32_e32 v64, v1
	v_mul_f32_e32 v1, 0xbfb8aa3b, v68
	v_exp_f32_e32 v1, v1
	s_nop 0
	v_add_f32_e32 v1, 1.0, v1
	v_rcp_f32_e32 v70, v1
	v_mul_f32_e32 v1, 0xbfb8aa3b, v61
	v_exp_f32_e32 v1, v1
	s_nop 0
	v_add_f32_e32 v1, 1.0, v1
	v_rcp_f32_e32 v65, v1
	v_mul_f32_e32 v1, 0xbfb8aa3b, v69
	v_exp_f32_e32 v1, v1
	v_pk_mul_f32 v[60:61], v[64:65], v[60:61]
	s_nop 0
	v_pk_mul_f32 v[58:59], v[60:61], v[58:59]
	v_add_f32_e32 v1, 1.0, v1
	v_rcp_f32_e32 v71, v1
	v_and_b32_e32 v61, 0xffff0000, v83
	v_and_b32_e32 v60, 0xffff0000, v82
	v_pk_mul_f32 v[60:61], v[62:63], v[60:61]
	v_pk_mul_f32 v[62:63], v[70:71], v[68:69]
	s_nop 0
	v_pk_mul_f32 v[60:61], v[62:63], v[60:61]
	s_nop 0
	v_cvt_pk_bf16_f32 v59, v59, v61
	v_add_f32_e32 v1, v46, v54
	v_mul_f32_e32 v1, 0xbfb8aa3b, v1
	v_exp_f32_e32 v1, v1
	v_cvt_pk_bf16_f32 v58, v58, v60
	v_add_f32_e32 v1, 1.0, v1
	v_rcp_f32_e32 v54, v1
	v_add_f32_e32 v1, v47, v55
	v_mul_f32_e32 v1, 0xbfb8aa3b, v1
	v_exp_f32_e32 v1, v1
	s_nop 0
	v_add_f32_e32 v1, 1.0, v1
	global_store_dwordx2 v[80:81], v[58:59], off offset:2592
	v_rcp_f32_e32 v58, v1
	v_add_f32_e32 v1, v48, v56
	v_mul_f32_e32 v1, 0xbfb8aa3b, v1
	v_exp_f32_e32 v1, v1
	v_lshlrev_b32_e32 v56, 16, v122
	v_and_b32_e32 v62, 0xffff0000, v122
	v_and_b32_e32 v63, 0xffff0000, v123
	v_add_f32_e32 v1, 1.0, v1
	v_rcp_f32_e32 v55, v1
	v_add_f32_e32 v1, v49, v57
	v_mul_f32_e32 v1, 0xbfb8aa3b, v1
	v_exp_f32_e32 v1, v1
	v_lshlrev_b32_e32 v57, 16, v123
	v_lshlrev_b32_e32 v69, 16, v87
	v_lshlrev_b32_e32 v68, 16, v86
	v_add_f32_e32 v1, 1.0, v1
	v_rcp_f32_e32 v59, v1
	v_mul_f32_e32 v1, 0xbfb8aa3b, v56
	v_exp_f32_e32 v1, v1
	v_pk_mul_f32 v[54:55], v[54:55], v[68:69]
	v_add_f32_e32 v1, 1.0, v1
	v_rcp_f32_e32 v60, v1
	v_mul_f32_e32 v1, 0xbfb8aa3b, v62
	v_exp_f32_e32 v1, v1
	s_nop 0
	v_add_f32_e32 v1, 1.0, v1
	v_rcp_f32_e32 v64, v1
	v_mul_f32_e32 v1, 0xbfb8aa3b, v57
	v_exp_f32_e32 v1, v1
	s_nop 0
	v_add_f32_e32 v1, 1.0, v1
	v_rcp_f32_e32 v61, v1
	v_mul_f32_e32 v1, 0xbfb8aa3b, v63
	v_exp_f32_e32 v1, v1
	v_pk_mul_f32 v[56:57], v[60:61], v[56:57]
	s_nop 0
	v_pk_mul_f32 v[54:55], v[56:57], v[54:55]
	v_add_f32_e32 v1, 1.0, v1
	v_rcp_f32_e32 v65, v1
	v_and_b32_e32 v57, 0xffff0000, v87
	v_and_b32_e32 v56, 0xffff0000, v86
	v_pk_mul_f32 v[56:57], v[58:59], v[56:57]
	v_pk_mul_f32 v[58:59], v[64:65], v[62:63]
	s_nop 0
	v_pk_mul_f32 v[56:57], v[58:59], v[56:57]
	s_nop 0
	v_cvt_pk_bf16_f32 v55, v55, v57
	v_add_f32_e32 v1, v46, v50
	v_mul_f32_e32 v1, 0xbfb8aa3b, v1
	v_exp_f32_e32 v1, v1
	v_cvt_pk_bf16_f32 v54, v54, v56
	v_add_f32_e32 v1, 1.0, v1
	v_rcp_f32_e32 v46, v1
	v_add_f32_e32 v1, v47, v51
	v_mul_f32_e32 v1, 0xbfb8aa3b, v1
	v_exp_f32_e32 v1, v1
	s_nop 0
	v_add_f32_e32 v1, 1.0, v1
	v_rcp_f32_e32 v50, v1
	v_add_f32_e32 v1, v48, v52
	v_mul_f32_e32 v1, 0xbfb8aa3b, v1
	v_exp_f32_e32 v1, v1
	v_lshlrev_b32_e32 v48, 16, v120
	global_store_dwordx2 v[84:85], v[54:55], off offset:2592
	v_and_b32_e32 v54, 0xffff0000, v120
	v_add_f32_e32 v1, 1.0, v1
	v_rcp_f32_e32 v47, v1
	v_add_f32_e32 v1, v49, v53
	v_mul_f32_e32 v1, 0xbfb8aa3b, v1
	v_exp_f32_e32 v1, v1
	v_lshlrev_b32_e32 v49, 16, v121
	v_and_b32_e32 v55, 0xffff0000, v121
	v_lshlrev_b32_e32 v59, 16, v77
	v_add_f32_e32 v1, 1.0, v1
	v_rcp_f32_e32 v51, v1
	v_mul_f32_e32 v1, 0xbfb8aa3b, v48
	v_exp_f32_e32 v1, v1
	v_lshlrev_b32_e32 v58, 16, v76
	v_pk_mul_f32 v[46:47], v[46:47], v[58:59]
	v_add_f32_e32 v1, 1.0, v1
	v_rcp_f32_e32 v52, v1
	v_mul_f32_e32 v1, 0xbfb8aa3b, v54
	v_exp_f32_e32 v1, v1
	s_nop 0
	v_add_f32_e32 v1, 1.0, v1
	v_rcp_f32_e32 v56, v1
	v_mul_f32_e32 v1, 0xbfb8aa3b, v49
	v_exp_f32_e32 v1, v1
	s_nop 0
	v_add_f32_e32 v1, 1.0, v1
	v_rcp_f32_e32 v53, v1
	v_mul_f32_e32 v1, 0xbfb8aa3b, v55
	v_exp_f32_e32 v1, v1
	v_pk_mul_f32 v[48:49], v[52:53], v[48:49]
	s_nop 0
	v_pk_mul_f32 v[46:47], v[48:49], v[46:47]
	v_add_f32_e32 v1, 1.0, v1
	v_rcp_f32_e32 v57, v1
	v_and_b32_e32 v49, 0xffff0000, v77
	v_and_b32_e32 v48, 0xffff0000, v76
	v_pk_mul_f32 v[48:49], v[50:51], v[48:49]
	v_pk_mul_f32 v[50:51], v[56:57], v[54:55]
	s_nop 0
	v_pk_mul_f32 v[48:49], v[50:51], v[48:49]
	s_nop 0
	v_cvt_pk_bf16_f32 v47, v47, v49
	v_add_f32_e32 v1, v26, v42
	v_mul_f32_e32 v1, 0xbfb8aa3b, v1
	v_exp_f32_e32 v1, v1
	v_cvt_pk_bf16_f32 v46, v46, v48
	v_add_f32_e32 v1, 1.0, v1
	v_rcp_f32_e32 v42, v1
	v_add_f32_e32 v1, v27, v43
	v_mul_f32_e32 v1, 0xbfb8aa3b, v1
	v_exp_f32_e32 v1, v1
	v_and_b32_e32 v54, 0xffff0000, v118
	v_and_b32_e32 v55, 0xffff0000, v119
	v_add_f32_e32 v1, 1.0, v1
	v_rcp_f32_e32 v50, v1
	v_add_f32_e32 v1, v28, v44
	v_mul_f32_e32 v1, 0xbfb8aa3b, v1
	v_exp_f32_e32 v1, v1
	v_lshlrev_b32_e32 v44, 16, v118
	v_add_f32_e32 v1, 1.0, v1
	v_rcp_f32_e32 v43, v1
	v_add_f32_e32 v1, v29, v45
	v_mul_f32_e32 v1, 0xbfb8aa3b, v1
	v_exp_f32_e32 v1, v1
	v_lshlrev_b32_e32 v45, 16, v119
	global_store_dwordx2 v[66:67], v[46:47], off offset:2592
	ds_read2_b64 v[46:49], v97 offset0:40 offset1:44
	v_add_f32_e32 v1, 1.0, v1
	v_rcp_f32_e32 v51, v1
	v_mul_f32_e32 v1, 0xbfb8aa3b, v44
	v_exp_f32_e32 v1, v1
	s_waitcnt lgkmcnt(0)
	v_lshlrev_b32_e32 v59, 16, v47
	v_lshlrev_b32_e32 v58, 16, v46
	v_pk_mul_f32 v[42:43], v[42:43], v[58:59]
	v_add_f32_e32 v1, 1.0, v1
	v_rcp_f32_e32 v52, v1
	v_mul_f32_e32 v1, 0xbfb8aa3b, v54
	v_exp_f32_e32 v1, v1
	s_nop 0
	v_add_f32_e32 v1, 1.0, v1
	v_rcp_f32_e32 v56, v1
	v_mul_f32_e32 v1, 0xbfb8aa3b, v45
	v_exp_f32_e32 v1, v1
	s_nop 0
	v_add_f32_e32 v1, 1.0, v1
	v_rcp_f32_e32 v53, v1
	v_mul_f32_e32 v1, 0xbfb8aa3b, v55
	v_exp_f32_e32 v1, v1
	v_pk_mul_f32 v[44:45], v[52:53], v[44:45]
	s_nop 0
	v_pk_mul_f32 v[42:43], v[44:45], v[42:43]
	v_add_f32_e32 v1, 1.0, v1
	v_rcp_f32_e32 v57, v1
	v_and_b32_e32 v45, 0xffff0000, v47
	v_and_b32_e32 v44, 0xffff0000, v46
	v_pk_mul_f32 v[44:45], v[50:51], v[44:45]
	v_pk_mul_f32 v[46:47], v[56:57], v[54:55]
	s_nop 0
	v_pk_mul_f32 v[44:45], v[46:47], v[44:45]
	s_nop 0
	v_cvt_pk_bf16_f32 v43, v43, v45
	v_add_f32_e32 v1, v26, v38
	v_mul_f32_e32 v1, 0xbfb8aa3b, v1
	v_exp_f32_e32 v1, v1
	v_cvt_pk_bf16_f32 v42, v42, v44
	v_add_f32_e32 v1, 1.0, v1
	global_store_dwordx2 v[88:89], v[42:43], off offset:2624
	v_rcp_f32_e32 v42, v1
	v_add_f32_e32 v1, v27, v39
	v_mul_f32_e32 v1, 0xbfb8aa3b, v1
	v_exp_f32_e32 v1, v1
	v_lshlrev_b32_e32 v46, 16, v116
	v_and_b32_e32 v52, 0xffff0000, v116
	v_lshlrev_b32_e32 v47, 16, v117
	v_add_f32_e32 v1, 1.0, v1
	v_rcp_f32_e32 v44, v1
	v_add_f32_e32 v1, v28, v40
	v_mul_f32_e32 v1, 0xbfb8aa3b, v1
	v_exp_f32_e32 v1, v1
	v_and_b32_e32 v53, 0xffff0000, v117
	v_add_f32_e32 v1, 1.0, v1
	v_rcp_f32_e32 v43, v1
	v_add_f32_e32 v1, v29, v41
	v_mul_f32_e32 v1, 0xbfb8aa3b, v1
	v_exp_f32_e32 v1, v1
	ds_read2_b64 v[38:41], v94 offset0:40 offset1:44
	v_add_f32_e32 v1, 1.0, v1
	v_rcp_f32_e32 v45, v1
	v_mul_f32_e32 v1, 0xbfb8aa3b, v46
	v_exp_f32_e32 v1, v1
	s_waitcnt lgkmcnt(0)
	v_lshlrev_b32_e32 v57, 16, v39
	v_lshlrev_b32_e32 v56, 16, v38
	v_pk_mul_f32 v[42:43], v[42:43], v[56:57]
	v_add_f32_e32 v1, 1.0, v1
	v_rcp_f32_e32 v50, v1
	v_mul_f32_e32 v1, 0xbfb8aa3b, v52
	v_exp_f32_e32 v1, v1
	v_and_b32_e32 v39, 0xffff0000, v39
	v_and_b32_e32 v38, 0xffff0000, v38
	v_pk_mul_f32 v[38:39], v[44:45], v[38:39]
	v_add_f32_e32 v1, 1.0, v1
	v_rcp_f32_e32 v54, v1
	v_mul_f32_e32 v1, 0xbfb8aa3b, v47
	v_exp_f32_e32 v1, v1
	s_nop 0
	v_add_f32_e32 v1, 1.0, v1
	v_rcp_f32_e32 v51, v1
	v_mul_f32_e32 v1, 0xbfb8aa3b, v53
	v_exp_f32_e32 v1, v1
	v_pk_mul_f32 v[46:47], v[50:51], v[46:47]
	s_nop 0
	v_pk_mul_f32 v[42:43], v[46:47], v[42:43]
	v_add_f32_e32 v1, 1.0, v1
	v_rcp_f32_e32 v55, v1
	v_and_b32_e32 v50, 0xffff0000, v114
	v_pk_mul_f32 v[44:45], v[54:55], v[52:53]
	v_and_b32_e32 v51, 0xffff0000, v115
	v_pk_mul_f32 v[38:39], v[44:45], v[38:39]
	s_nop 0
	v_cvt_pk_bf16_f32 v39, v43, v39
	v_add_f32_e32 v1, v26, v34
	v_mul_f32_e32 v1, 0xbfb8aa3b, v1
	v_exp_f32_e32 v1, v1
	v_cvt_pk_bf16_f32 v42, v42, v42
	v_cvt_pk_bf16_f32 v38, v38, v38
	v_add_f32_e32 v1, 1.0, v1
	v_rcp_f32_e32 v34, v1
	v_add_f32_e32 v1, v27, v35
	v_mul_f32_e32 v1, 0xbfb8aa3b, v1
	v_exp_f32_e32 v1, v1
	v_bfi_b32 v38, s33, v38, v42
	v_lshlrev_b32_e32 v44, 16, v114
	v_add_f32_e32 v1, 1.0, v1
	v_rcp_f32_e32 v42, v1
	v_add_f32_e32 v1, v28, v36
	v_mul_f32_e32 v1, 0xbfb8aa3b, v1
	v_exp_f32_e32 v1, v1
	v_lshlrev_b32_e32 v45, 16, v115
	global_store_dwordx2 v[80:81], v[38:39], off offset:2624
	v_add_f32_e32 v1, 1.0, v1
	v_rcp_f32_e32 v35, v1
	v_add_f32_e32 v1, v29, v37
	v_mul_f32_e32 v1, 0xbfb8aa3b, v1
	v_exp_f32_e32 v1, v1
	ds_read2_b64 v[36:39], v95 offset0:40 offset1:44
	v_add_f32_e32 v1, 1.0, v1
	v_rcp_f32_e32 v43, v1
	v_mul_f32_e32 v1, 0xbfb8aa3b, v44
	v_exp_f32_e32 v1, v1
	s_waitcnt lgkmcnt(0)
	v_lshlrev_b32_e32 v55, 16, v37
	v_lshlrev_b32_e32 v54, 16, v36
	v_pk_mul_f32 v[34:35], v[34:35], v[54:55]
	v_add_f32_e32 v1, 1.0, v1
	v_rcp_f32_e32 v46, v1
	v_mul_f32_e32 v1, 0xbfb8aa3b, v50
	v_exp_f32_e32 v1, v1
	v_and_b32_e32 v37, 0xffff0000, v37
	v_and_b32_e32 v36, 0xffff0000, v36
	v_pk_mul_f32 v[36:37], v[42:43], v[36:37]
	v_add_f32_e32 v1, 1.0, v1
	v_rcp_f32_e32 v52, v1
	v_mul_f32_e32 v1, 0xbfb8aa3b, v45
	v_exp_f32_e32 v1, v1
	s_nop 0
	v_add_f32_e32 v1, 1.0, v1
	v_rcp_f32_e32 v47, v1
	v_mul_f32_e32 v1, 0xbfb8aa3b, v51
	v_exp_f32_e32 v1, v1
	v_pk_mul_f32 v[44:45], v[46:47], v[44:45]
	s_nop 0
	v_pk_mul_f32 v[34:35], v[44:45], v[34:35]
	v_add_f32_e32 v1, 1.0, v1
	v_rcp_f32_e32 v53, v1
	s_nop 0
	v_pk_mul_f32 v[42:43], v[52:53], v[50:51]
	s_nop 0
	v_pk_mul_f32 v[36:37], v[42:43], v[36:37]
	s_nop 0
	v_cvt_pk_bf16_f32 v35, v35, v37
	v_add_f32_e32 v1, v26, v30
	v_mul_f32_e32 v1, 0xbfb8aa3b, v1
	v_exp_f32_e32 v1, v1
	v_cvt_pk_bf16_f32 v34, v34, v34
	v_cvt_pk_bf16_f32 v36, v36, v36
	v_add_f32_e32 v1, 1.0, v1
	v_rcp_f32_e32 v26, v1
	v_add_f32_e32 v1, v27, v31
	v_mul_f32_e32 v1, 0xbfb8aa3b, v1
	v_exp_f32_e32 v1, v1
	v_and_b32_e32 v42, 0xffff0000, v112
	v_and_b32_e32 v43, 0xffff0000, v113
	v_add_f32_e32 v1, 1.0, v1
	v_rcp_f32_e32 v30, v1
	v_add_f32_e32 v1, v28, v32
	v_mul_f32_e32 v1, 0xbfb8aa3b, v1
	v_exp_f32_e32 v1, v1
	v_lshlrev_b32_e32 v28, 16, v112
	v_bfi_b32 v34, s33, v36, v34
	global_store_dwordx2 v[84:85], v[34:35], off offset:2624
	v_add_f32_e32 v1, 1.0, v1
	v_rcp_f32_e32 v27, v1
	v_add_f32_e32 v1, v29, v33
	v_mul_f32_e32 v1, 0xbfb8aa3b, v1
	v_exp_f32_e32 v1, v1
	v_lshlrev_b32_e32 v29, 16, v113
	ds_read2_b64 v[34:37], v96 offset0:72 offset1:76
	v_add_f32_e32 v1, 1.0, v1
	v_rcp_f32_e32 v31, v1
	v_mul_f32_e32 v1, 0xbfb8aa3b, v28
	v_exp_f32_e32 v1, v1
	s_waitcnt lgkmcnt(0)
	v_lshlrev_b32_e32 v47, 16, v35
	v_lshlrev_b32_e32 v46, 16, v34
	v_pk_mul_f32 v[26:27], v[26:27], v[46:47]
	v_add_f32_e32 v1, 1.0, v1
	v_rcp_f32_e32 v32, v1
	v_mul_f32_e32 v1, 0xbfb8aa3b, v42
	v_exp_f32_e32 v1, v1
	s_nop 0
	v_add_f32_e32 v1, 1.0, v1
	v_rcp_f32_e32 v44, v1
	v_mul_f32_e32 v1, 0xbfb8aa3b, v29
	v_exp_f32_e32 v1, v1
	s_nop 0
	v_add_f32_e32 v1, 1.0, v1
	v_rcp_f32_e32 v33, v1
	v_mul_f32_e32 v1, 0xbfb8aa3b, v43
	v_exp_f32_e32 v1, v1
	v_pk_mul_f32 v[28:29], v[32:33], v[28:29]
	s_nop 0
	v_pk_mul_f32 v[26:27], v[28:29], v[26:27]
	v_add_f32_e32 v1, 1.0, v1
	v_rcp_f32_e32 v45, v1
	v_and_b32_e32 v29, 0xffff0000, v35
	v_and_b32_e32 v28, 0xffff0000, v34
	v_pk_mul_f32 v[28:29], v[30:31], v[28:29]
	v_pk_mul_f32 v[30:31], v[44:45], v[42:43]
	s_nop 0
	v_pk_mul_f32 v[28:29], v[30:31], v[28:29]
	s_nop 0
	v_cvt_pk_bf16_f32 v27, v27, v29
	v_add_f32_e32 v1, v6, v22
	v_mul_f32_e32 v1, 0xbfb8aa3b, v1
	v_exp_f32_e32 v1, v1
	v_cvt_pk_bf16_f32 v26, v26, v28
	v_add_f32_e32 v1, 1.0, v1
	v_rcp_f32_e32 v22, v1
	v_add_f32_e32 v1, v7, v23
	v_mul_f32_e32 v1, 0xbfb8aa3b, v1
	v_exp_f32_e32 v1, v1
	s_nop 0
	v_add_f32_e32 v1, 1.0, v1
	global_store_dwordx2 v[66:67], v[26:27], off offset:2624
	v_rcp_f32_e32 v26, v1
	v_add_f32_e32 v1, v8, v24
	v_mul_f32_e32 v1, 0xbfb8aa3b, v1
	v_exp_f32_e32 v1, v1
	v_lshlrev_b32_e32 v24, 16, v110
	v_and_b32_e32 v30, 0xffff0000, v110
	v_and_b32_e32 v31, 0xffff0000, v111
	v_add_f32_e32 v1, 1.0, v1
	v_rcp_f32_e32 v23, v1
	v_add_f32_e32 v1, v9, v25
	v_mul_f32_e32 v1, 0xbfb8aa3b, v1
	v_exp_f32_e32 v1, v1
	v_lshlrev_b32_e32 v25, 16, v111
	v_lshlrev_b32_e32 v35, 16, v49
	v_lshlrev_b32_e32 v34, 16, v48
	v_add_f32_e32 v1, 1.0, v1
	v_rcp_f32_e32 v27, v1
	v_mul_f32_e32 v1, 0xbfb8aa3b, v24
	v_exp_f32_e32 v1, v1
	v_pk_mul_f32 v[22:23], v[22:23], v[34:35]
	v_add_f32_e32 v1, 1.0, v1
	v_rcp_f32_e32 v28, v1
	v_mul_f32_e32 v1, 0xbfb8aa3b, v30
	v_exp_f32_e32 v1, v1
	s_nop 0
	v_add_f32_e32 v1, 1.0, v1
	v_rcp_f32_e32 v32, v1
	v_mul_f32_e32 v1, 0xbfb8aa3b, v25
	v_exp_f32_e32 v1, v1
	s_nop 0
	v_add_f32_e32 v1, 1.0, v1
	v_rcp_f32_e32 v29, v1
	v_mul_f32_e32 v1, 0xbfb8aa3b, v31
	v_exp_f32_e32 v1, v1
	v_pk_mul_f32 v[24:25], v[28:29], v[24:25]
	s_nop 0
	v_pk_mul_f32 v[22:23], v[24:25], v[22:23]
	v_add_f32_e32 v1, 1.0, v1
	v_rcp_f32_e32 v33, v1
	v_and_b32_e32 v25, 0xffff0000, v49
	v_and_b32_e32 v24, 0xffff0000, v48
	v_pk_mul_f32 v[24:25], v[26:27], v[24:25]
	v_pk_mul_f32 v[26:27], v[32:33], v[30:31]
	s_nop 0
	v_pk_mul_f32 v[24:25], v[26:27], v[24:25]
	s_nop 0
	v_cvt_pk_bf16_f32 v23, v23, v25
	v_add_f32_e32 v1, v6, v18
	v_mul_f32_e32 v1, 0xbfb8aa3b, v1
	v_exp_f32_e32 v1, v1
	v_cvt_pk_bf16_f32 v22, v22, v24
	v_add_f32_e32 v1, 1.0, v1
	v_rcp_f32_e32 v18, v1
	v_add_f32_e32 v1, v7, v19
	v_mul_f32_e32 v1, 0xbfb8aa3b, v1
	v_exp_f32_e32 v1, v1
	s_nop 0
	v_add_f32_e32 v1, 1.0, v1
	global_store_dwordx2 v[88:89], v[22:23], off offset:2656
	v_rcp_f32_e32 v22, v1
	v_add_f32_e32 v1, v8, v20
	v_mul_f32_e32 v1, 0xbfb8aa3b, v1
	v_exp_f32_e32 v1, v1
	v_lshlrev_b32_e32 v20, 16, v108
	v_and_b32_e32 v26, 0xffff0000, v108
	v_and_b32_e32 v27, 0xffff0000, v109
	v_add_f32_e32 v1, 1.0, v1
	v_rcp_f32_e32 v19, v1
	v_add_f32_e32 v1, v9, v21
	v_mul_f32_e32 v1, 0xbfb8aa3b, v1
	v_exp_f32_e32 v1, v1
	v_lshlrev_b32_e32 v21, 16, v109
	v_lshlrev_b32_e32 v31, 16, v41
	v_lshlrev_b32_e32 v30, 16, v40
	v_add_f32_e32 v1, 1.0, v1
	v_rcp_f32_e32 v23, v1
	v_mul_f32_e32 v1, 0xbfb8aa3b, v20
	v_exp_f32_e32 v1, v1
	v_pk_mul_f32 v[18:19], v[18:19], v[30:31]
	v_add_f32_e32 v1, 1.0, v1
	v_rcp_f32_e32 v24, v1
	v_mul_f32_e32 v1, 0xbfb8aa3b, v26
	v_exp_f32_e32 v1, v1
	s_nop 0
	v_add_f32_e32 v1, 1.0, v1
	v_rcp_f32_e32 v28, v1
	v_mul_f32_e32 v1, 0xbfb8aa3b, v21
	v_exp_f32_e32 v1, v1
	s_nop 0
	v_add_f32_e32 v1, 1.0, v1
	v_rcp_f32_e32 v25, v1
	v_mul_f32_e32 v1, 0xbfb8aa3b, v27
	v_exp_f32_e32 v1, v1
	v_pk_mul_f32 v[20:21], v[24:25], v[20:21]
	s_nop 0
	v_pk_mul_f32 v[18:19], v[20:21], v[18:19]
	v_add_f32_e32 v1, 1.0, v1
	v_rcp_f32_e32 v29, v1
	v_and_b32_e32 v21, 0xffff0000, v41
	v_and_b32_e32 v20, 0xffff0000, v40
	v_pk_mul_f32 v[20:21], v[22:23], v[20:21]
	v_pk_mul_f32 v[22:23], v[28:29], v[26:27]
	s_nop 0
	v_pk_mul_f32 v[20:21], v[22:23], v[20:21]
	s_nop 0
	v_cvt_pk_bf16_f32 v19, v19, v21
	v_add_f32_e32 v1, v6, v14
	v_mul_f32_e32 v1, 0xbfb8aa3b, v1
	v_exp_f32_e32 v1, v1
	v_cvt_pk_bf16_f32 v18, v18, v20
	v_add_f32_e32 v1, 1.0, v1
	v_rcp_f32_e32 v14, v1
	v_add_f32_e32 v1, v7, v15
	v_mul_f32_e32 v1, 0xbfb8aa3b, v1
	v_exp_f32_e32 v1, v1
	s_nop 0
	v_add_f32_e32 v1, 1.0, v1
	global_store_dwordx2 v[80:81], v[18:19], off offset:2656
	v_rcp_f32_e32 v18, v1
	v_add_f32_e32 v1, v8, v16
	v_mul_f32_e32 v1, 0xbfb8aa3b, v1
	v_exp_f32_e32 v1, v1
	v_lshlrev_b32_e32 v16, 16, v106
	v_and_b32_e32 v22, 0xffff0000, v106
	v_and_b32_e32 v23, 0xffff0000, v107
	v_add_f32_e32 v1, 1.0, v1
	v_rcp_f32_e32 v15, v1
	v_add_f32_e32 v1, v9, v17
	v_mul_f32_e32 v1, 0xbfb8aa3b, v1
	v_exp_f32_e32 v1, v1
	v_lshlrev_b32_e32 v17, 16, v107
	v_lshlrev_b32_e32 v27, 16, v39
	v_lshlrev_b32_e32 v26, 16, v38
	v_add_f32_e32 v1, 1.0, v1
	v_rcp_f32_e32 v19, v1
	v_mul_f32_e32 v1, 0xbfb8aa3b, v16
	v_exp_f32_e32 v1, v1
	v_pk_mul_f32 v[14:15], v[14:15], v[26:27]
	v_add_f32_e32 v1, 1.0, v1
	v_rcp_f32_e32 v20, v1
	v_mul_f32_e32 v1, 0xbfb8aa3b, v22
	v_exp_f32_e32 v1, v1
	s_nop 0
	v_add_f32_e32 v1, 1.0, v1
	v_rcp_f32_e32 v24, v1
	v_mul_f32_e32 v1, 0xbfb8aa3b, v17
	v_exp_f32_e32 v1, v1
	s_nop 0
	v_add_f32_e32 v1, 1.0, v1
	v_rcp_f32_e32 v21, v1
	v_mul_f32_e32 v1, 0xbfb8aa3b, v23
	v_exp_f32_e32 v1, v1
	v_pk_mul_f32 v[16:17], v[20:21], v[16:17]
	s_nop 0
	v_pk_mul_f32 v[14:15], v[16:17], v[14:15]
	v_add_f32_e32 v1, 1.0, v1
	v_rcp_f32_e32 v25, v1
	v_and_b32_e32 v17, 0xffff0000, v39
	v_and_b32_e32 v16, 0xffff0000, v38
	v_pk_mul_f32 v[16:17], v[18:19], v[16:17]
	v_pk_mul_f32 v[18:19], v[24:25], v[22:23]
	s_nop 0
	v_pk_mul_f32 v[16:17], v[18:19], v[16:17]
	s_nop 0
	v_cvt_pk_bf16_f32 v15, v15, v17
	v_add_f32_e32 v1, v6, v10
	v_mul_f32_e32 v1, 0xbfb8aa3b, v1
	v_exp_f32_e32 v1, v1
	v_cvt_pk_bf16_f32 v14, v14, v16
	v_add_f32_e32 v1, 1.0, v1
	v_rcp_f32_e32 v6, v1
	v_add_f32_e32 v1, v7, v11
	v_mul_f32_e32 v1, 0xbfb8aa3b, v1
	v_exp_f32_e32 v1, v1
	s_nop 0
	v_add_f32_e32 v1, 1.0, v1
	v_rcp_f32_e32 v10, v1
	v_add_f32_e32 v1, v8, v12
	v_mul_f32_e32 v1, 0xbfb8aa3b, v1
	v_exp_f32_e32 v1, v1
	v_lshlrev_b32_e32 v8, 16, v104
	global_store_dwordx2 v[84:85], v[14:15], off offset:2656
	v_and_b32_e32 v14, 0xffff0000, v104
	v_add_f32_e32 v1, 1.0, v1
	v_rcp_f32_e32 v7, v1
	v_add_f32_e32 v1, v9, v13
	v_mul_f32_e32 v1, 0xbfb8aa3b, v1
	v_exp_f32_e32 v1, v1
	v_lshlrev_b32_e32 v9, 16, v105
	v_and_b32_e32 v15, 0xffff0000, v105
	v_lshlrev_b32_e32 v19, 16, v37
	v_add_f32_e32 v1, 1.0, v1
	v_rcp_f32_e32 v11, v1
	v_mul_f32_e32 v1, 0xbfb8aa3b, v8
	v_exp_f32_e32 v1, v1
	v_lshlrev_b32_e32 v18, 16, v36
	v_pk_mul_f32 v[6:7], v[6:7], v[18:19]
	v_add_f32_e32 v1, 1.0, v1
	v_rcp_f32_e32 v12, v1
	v_mul_f32_e32 v1, 0xbfb8aa3b, v14
	v_exp_f32_e32 v1, v1
	s_nop 0
	v_add_f32_e32 v1, 1.0, v1
	v_rcp_f32_e32 v16, v1
	v_mul_f32_e32 v1, 0xbfb8aa3b, v9
	v_exp_f32_e32 v1, v1
	s_nop 0
	v_add_f32_e32 v1, 1.0, v1
	v_rcp_f32_e32 v13, v1
	v_mul_f32_e32 v1, 0xbfb8aa3b, v15
	v_exp_f32_e32 v1, v1
	v_pk_mul_f32 v[8:9], v[12:13], v[8:9]
	s_nop 0
	v_pk_mul_f32 v[6:7], v[8:9], v[6:7]
	v_add_f32_e32 v1, 1.0, v1
	v_rcp_f32_e32 v17, v1
	v_and_b32_e32 v9, 0xffff0000, v37
	v_and_b32_e32 v8, 0xffff0000, v36
	v_pk_mul_f32 v[8:9], v[10:11], v[8:9]
	v_pk_mul_f32 v[10:11], v[16:17], v[14:15]
	s_nop 0
	v_pk_mul_f32 v[8:9], v[10:11], v[8:9]
	s_nop 0
	v_cvt_pk_bf16_f32 v7, v7, v9
	v_cvt_pk_bf16_f32 v6, v6, v8
	global_store_dwordx2 v[66:67], v[6:7], off offset:2656
	s_barrier

.LBB0_776:
	s_ashr_i32 s0, s6, 7
	s_ashr_i32 s1, s0, 31
	s_lshl_b64 s[8:9], s[0:1], 20
	s_add_u32 s8, s56, s8
	s_addc_u32 s9, s57, s9
	s_lshl_b64 s[0:1], s[0:1], 19
	s_add_u32 s0, s20, s0
	s_addc_u32 s1, s28, s1
	s_lshl_b32 s7, s6, 2
	s_and_b32 s7, s7, 0x1c0
	v_or_b32_e32 v10, s7, v45
	s_and_b32 s10, s5, 0x1e0
	v_lshlrev_b32_e32 v10, 9, v10
	v_or3_b32 v10, v10, v44, s10
	v_lshlrev_b32_e32 v138, 2, v10
	v_lshl_add_u64 v[12:13], s[8:9], 0, v[138:139]
	v_add_co_u32_e32 v14, vcc, s68, v12
	s_lshl_b32 s7, s7, 5
	s_nop 0
	v_addc_co_u32_e32 v15, vcc, 0, v13, vcc
	v_add_co_u32_e32 v16, vcc, s69, v12
	s_add_u32 s0, s0, s7
	s_nop 0
	v_addc_co_u32_e32 v17, vcc, 0, v13, vcc
	v_add_co_u32_e32 v18, vcc, s70, v12
	s_waitcnt lgkmcnt(0)
	v_mov_b32_e32 v7, v139
	v_addc_co_u32_e32 v19, vcc, 0, v13, vcc
	v_add_co_u32_e32 v20, vcc, s19, v12
	s_addc_u32 s1, s1, 0
	s_nop 0
	v_addc_co_u32_e32 v21, vcc, 0, v13, vcc
	v_add_co_u32_e32 v22, vcc, s16, v12
	v_lshrrev_b32_e32 v76, 6, v6
	v_and_b32_e32 v78, 0x30, v6
	v_lshlrev_b32_e32 v76, 10, v76
	v_mov_b32_e32 v77, 0
	v_or_b32_e32 v76, v76, v78
	v_lshl_add_u64 v[10:11], s[0:1], 0, v[76:77]
	s_nop 0
	v_addc_co_u32_e32 v23, vcc, 0, v13, vcc
	v_add_co_u32_e32 v24, vcc, s27, v12
	s_mov_b32 s0, 0x1f000
	s_nop 0
	v_addc_co_u32_e32 v25, vcc, 0, v13, vcc
	v_add_co_u32_e32 v26, vcc, s22, v12
	global_load_dword v7, v138, s[8:9]
	s_nop 0
	v_addc_co_u32_e32 v27, vcc, 0, v13, vcc
	v_add_co_u32_e32 v28, vcc, s24, v12
	v_or_b32_e32 v62, s10, v46
	s_nop 0
	v_addc_co_u32_e32 v29, vcc, 0, v13, vcc
	v_add_co_u32_e32 v30, vcc, s29, v12
	v_or_b32_e32 v63, s10, v47
	s_nop 0
	v_addc_co_u32_e32 v31, vcc, 0, v13, vcc
	v_add_co_u32_e32 v32, vcc, s18, v12
	v_lshrrev_b32_e32 v138, 4, v62
	v_and_b32_e32 v78, 15, v62
	v_lshlrev_b32_e32 v138, 14, v138
	v_lshl_or_b32 v138, v78, 6, v138
	s_nop 0
	v_addc_co_u32_e32 v33, vcc, 0, v13, vcc
	v_add_co_u32_e32 v34, vcc, s25, v12
	v_or_b32_e32 v64, s10, v48
	s_nop 0
	v_addc_co_u32_e32 v35, vcc, 0, v13, vcc
	v_add_co_u32_e32 v36, vcc, s30, v12
	v_add_u32_e32 v55, 0x400, v53
	s_nop 0
	v_addc_co_u32_e32 v37, vcc, 0, v13, vcc
	v_add_co_u32_e32 v38, vcc, s23, v12
	v_add_u32_e32 v56, 0x800, v53
	s_nop 0
	v_addc_co_u32_e32 v39, vcc, 0, v13, vcc
	v_add_co_u32_e32 v40, vcc, s17, v12
	v_add_u32_e32 v57, 0xc00, v53
	s_nop 0
	v_addc_co_u32_e32 v41, vcc, 0, v13, vcc
	v_add_co_u32_e32 v42, vcc, s90, v12
	v_add_u32_e32 v58, 0x1000, v53
	s_nop 0
	v_addc_co_u32_e32 v43, vcc, 0, v13, vcc
	v_add_co_u32_e32 v12, vcc, s0, v12
	v_add_u32_e32 v59, 0x1400, v53
	s_nop 0
	v_addc_co_u32_e32 v13, vcc, 0, v13, vcc
	global_load_dword v66, v[14:15], off offset:-4096
	s_nop 0
	global_load_dword v14, v[14:15], off
	s_nop 0
	global_load_dword v15, v[16:17], off offset:-4096
	s_nop 0
	global_load_dword v16, v[16:17], off
	s_nop 0
	global_load_dword v17, v[18:19], off offset:-4096
	s_nop 0
	global_load_dword v18, v[18:19], off
	s_nop 0
	global_load_dword v19, v[20:21], off offset:-4096
	s_nop 0
	global_load_dword v20, v[20:21], off
	s_nop 0
	global_load_dword v21, v[22:23], off offset:-4096
	s_nop 0
	global_load_dword v22, v[22:23], off
	s_nop 0
	global_load_dword v23, v[24:25], off offset:-4096
	s_nop 0
	global_load_dword v24, v[24:25], off
	s_nop 0
	global_load_dword v25, v[26:27], off offset:-4096
	global_load_dword v67, v[26:27], off
	global_load_dword v68, v[28:29], off offset:-4096
	global_load_dword v69, v[28:29], off
	global_load_dword v70, v[30:31], off offset:-4096
	global_load_dword v71, v[30:31], off
	global_load_dword v72, v[32:33], off offset:-4096
	global_load_dword v73, v[32:33], off
	global_load_dword v74, v[34:35], off offset:-4096
	s_nop 0
	global_load_dword v34, v[34:35], off
	s_nop 0
	global_load_dword v35, v[36:37], off offset:-4096
	s_nop 0
	global_load_dword v36, v[36:37], off
	s_nop 0
	global_load_dword v37, v[38:39], off offset:-4096
	s_nop 0
	global_load_dword v38, v[38:39], off
	s_nop 0
	global_load_dword v39, v[40:41], off offset:-4096
	s_nop 0
	global_load_dword v40, v[40:41], off
	s_nop 0
	global_load_dword v41, v[42:43], off offset:-4096
	s_nop 0
	global_load_dword v42, v[42:43], off
	s_nop 0
	global_load_dword v12, v[12:13], off
	v_lshl_add_u64 v[26:27], v[10:11], 0, v[138:139]
	v_lshrrev_b32_e32 v138, 4, v63
	v_and_b32_e32 v78, 15, v63
	v_lshlrev_b32_e32 v138, 14, v138
	v_lshl_or_b32 v138, v78, 6, v138
	v_add_u32_e32 v60, 0x1800, v53
	v_add_u32_e32 v61, 0x1c00, v53
	v_or_b32_e32 v65, s10, v49
	v_lshl_add_u64 v[28:29], v[10:11], 0, v[138:139]
	v_lshrrev_b32_e32 v138, 4, v64
	v_and_b32_e32 v78, 15, v64
	v_lshlrev_b32_e32 v138, 14, v138
	v_lshl_or_b32 v138, v78, 6, v138
	v_lshl_add_u64 v[30:31], v[10:11], 0, v[138:139]
	v_lshrrev_b32_e32 v138, 4, v65
	v_and_b32_e32 v78, 15, v65
	v_lshlrev_b32_e32 v138, 14, v138
	v_lshl_or_b32 v138, v78, 6, v138
	v_lshl_add_u64 v[32:33], v[10:11], 0, v[138:139]
	s_add_i32 s6, s6, s12
	s_add_i32 s5, s5, s96
	s_cmpk_gt_i32 s6, 0x1ff
	s_waitcnt vmcnt(0)
	ds_write2_b32 v53, v7, v66 offset1:66
	ds_write2_b32 v53, v14, v15 offset0:132 offset1:198
	ds_write2_b32 v55, v16, v17 offset0:8 offset1:74
	ds_write2_b32 v55, v18, v19 offset0:140 offset1:206
	ds_write2_b32 v56, v20, v21 offset0:16 offset1:82
	ds_write2_b32 v56, v22, v23 offset0:148 offset1:214
	ds_write2_b32 v57, v24, v25 offset0:24 offset1:90
	ds_write2_b32 v57, v67, v68 offset0:156 offset1:222
	ds_write2_b32 v58, v69, v70 offset0:32 offset1:98
	ds_write2_b32 v58, v71, v72 offset0:164 offset1:230
	ds_write2_b32 v59, v73, v74 offset0:40 offset1:106
	ds_write2_b32 v59, v34, v35 offset0:172 offset1:238
	ds_write2_b32 v60, v36, v37 offset0:48 offset1:114
	ds_write2_b32 v60, v38, v39 offset0:180 offset1:246
	ds_write2_b32 v61, v40, v41 offset0:56 offset1:122
	ds_write2_b32 v61, v42, v12 offset0:188 offset1:254
	s_waitcnt lgkmcnt(0)
	ds_read2_b32 v[10:11], v52 offset0:33 offset1:41
	ds_read2_b32 v[12:13], v52 offset1:8
	ds_read2_b32 v[14:15], v52 offset0:66 offset1:74
	ds_read2_b32 v[16:17], v52 offset0:99 offset1:107
	ds_read2_b32 v[18:19], v52 offset0:132 offset1:140
	ds_read2_b32 v[20:21], v52 offset0:165 offset1:173
	ds_read2_b32 v[22:23], v52 offset0:198 offset1:206
	ds_read2_b32 v[24:25], v52 offset0:231 offset1:239
	ds_read2_b32 v[34:35], v52 offset0:49 offset1:57
	ds_read2_b32 v[36:37], v52 offset0:16 offset1:24
	ds_read2_b32 v[38:39], v52 offset0:82 offset1:90
	ds_read2_b32 v[40:41], v52 offset0:115 offset1:123
	ds_read2_b32 v[42:43], v52 offset0:148 offset1:156
	ds_read2_b32 v[56:57], v52 offset0:181 offset1:189
	ds_read2_b32 v[58:59], v52 offset0:214 offset1:222
	ds_read2_b32 v[60:61], v52 offset0:247 offset1:255
	s_waitcnt lgkmcnt(14)
	s_waitcnt lgkmcnt(13)
	s_waitcnt lgkmcnt(12)
	s_waitcnt lgkmcnt(11)
	s_waitcnt lgkmcnt(10)
	s_waitcnt lgkmcnt(9)
	s_waitcnt lgkmcnt(8)
	v_cvt_pk_bf16_f32 v15, v15, v17
	s_waitcnt lgkmcnt(6)
	s_waitcnt lgkmcnt(5)
	s_waitcnt lgkmcnt(4)
	s_waitcnt lgkmcnt(3)
	s_waitcnt lgkmcnt(1)
	v_cvt_pk_bf16_f32 v7, v12, v12
	v_cvt_pk_bf16_f32 v12, v14, v14
	v_cvt_pk_bf16_f32 v14, v16, v16
	v_cvt_pk_bf16_f32 v16, v18, v18
	v_cvt_pk_bf16_f32 v18, v20, v20
	v_cvt_pk_bf16_f32 v20, v22, v22
	s_waitcnt lgkmcnt(0)
	v_cvt_pk_bf16_f32 v10, v10, v10
	v_cvt_pk_bf16_f32 v22, v24, v24
	v_cvt_pk_bf16_f32 v13, v13, v13
	v_cvt_pk_bf16_f32 v24, v11, v11
	v_cvt_pk_bf16_f32 v17, v19, v19
	v_cvt_pk_bf16_f32 v19, v21, v21
	v_cvt_pk_bf16_f32 v21, v23, v23
	v_cvt_pk_bf16_f32 v23, v25, v25
	v_cvt_pk_bf16_f32 v25, v36, v36
	v_cvt_pk_bf16_f32 v36, v38, v38
	v_cvt_pk_bf16_f32 v38, v40, v40
	v_cvt_pk_bf16_f32 v40, v42, v42
	v_cvt_pk_bf16_f32 v55, v58, v58
	v_cvt_pk_bf16_f32 v37, v37, v37
	v_cvt_pk_bf16_f32 v39, v39, v39
	v_cvt_pk_bf16_f32 v43, v43, v43
	v_cvt_pk_bf16_f32 v58, v59, v59
	v_cvt_pk_bf16_f32 v34, v34, v34
	v_cvt_pk_bf16_f32 v42, v56, v56
	v_cvt_pk_bf16_f32 v56, v60, v60
	v_cvt_pk_bf16_f32 v35, v35, v35
	v_cvt_pk_bf16_f32 v41, v41, v41
	v_cvt_pk_bf16_f32 v57, v57, v57
	v_cvt_pk_bf16_f32 v59, v61, v61
	v_lshrrev_b32_e32 v60, 16, v13
	v_bfi_b32 v10, s33, v10, v7
	v_bfi_b32 v11, s33, v14, v12
	v_bfi_b32 v12, s33, v18, v16
	v_bfi_b32 v13, s33, v22, v20
	v_and_or_b32 v14, v24, s33, v60
	v_bfi_b32 v16, s33, v19, v17
	v_bfi_b32 v17, s33, v23, v21
	v_bfi_b32 v18, s33, v34, v25
	v_bfi_b32 v19, s33, v38, v36
	v_bfi_b32 v20, s33, v42, v40
	v_bfi_b32 v21, s33, v56, v55
	v_bfi_b32 v22, s33, v35, v37
	v_bfi_b32 v23, s33, v41, v39
	v_bfi_b32 v24, s33, v57, v43
	v_bfi_b32 v25, s33, v59, v58
	global_store_dwordx4 v[26:27], v[10:13], off
	global_store_dwordx4 v[28:29], v[14:17], off
	global_store_dwordx4 v[30:31], v[18:21], off
	global_store_dwordx4 v[32:33], v[22:25], off
	s_waitcnt lgkmcnt(0)
	s_cbranch_scc0 .LBB0_776
